# GEMM K-loops: the mid-segment s_setprio 0 / s_setprio 1 flip pairs deleted (32 sites), on the v042 stack
# baseline (speedup 1.0000x reference)
.LBB0_290:
	ds_read_b128 v[154:157], v150
	ds_read_b128 v[158:161], v150 offset:1024
	ds_read_b128 v[162:165], v150 offset:2048
	ds_read_b128 v[166:169], v150 offset:3072
	ds_read_b128 v[170:173], v151
	ds_read_b128 v[174:177], v151 offset:1024
	ds_read_b128 v[178:181], v151 offset:2048
	ds_read_b128 v[182:185], v151 offset:3072
	s_add_u32 s44, s50, 0xfff00080
	s_addc_u32 s45, s51, -1
	s_cmp_eq_u32 s74, 60
	s_cselect_b32 s55, s37, s45
	s_cselect_b32 s54, s70, s44
	s_cselect_b32 s53, s27, s73
	s_cselect_b32 s52, s71, s72
	v_lshl_add_u64 v[146:147], s[50:51], 0, v[138:139]
	s_add_i32 m0, s43, 0xc000
	ds_read_b128 v[186:189], v152
	ds_read_b128 v[190:193], v152 offset:1024
	ds_read_b128 v[194:197], v152 offset:2048
	ds_read_b128 v[198:201], v152 offset:3072
	ds_read_b128 v[202:205], v152 offset:4096
	ds_read_b128 v[206:209], v152 offset:5120
	ds_read_b128 v[210:213], v152 offset:6144
	ds_read_b128 v[214:217], v152 offset:7168
	global_load_lds_dwordx4 v[146:147], off
	v_lshl_add_u64 v[146:147], s[50:51], 0, v[140:141]
	s_add_i32 m0, s43, 0xe000
	s_nop 0
	global_load_lds_dwordx4 v[146:147], off
	s_waitcnt vmcnt(8)
	s_waitcnt lgkmcnt(0)
	s_barrier
	s_setprio 1
	s_waitcnt lgkmcnt(0)
	v_mfma_f32_16x16x32_bf16 v[126:129], v[154:157], v[186:189], v[126:129]
	v_mfma_f32_16x16x32_bf16 v[122:125], v[162:165], v[186:189], v[122:125]
	v_mfma_f32_16x16x32_bf16 v[118:121], v[154:157], v[194:197], v[118:121]
	v_mfma_f32_16x16x32_bf16 v[110:113], v[162:165], v[194:197], v[110:113]
	v_mfma_f32_16x16x32_bf16 v[102:105], v[154:157], v[202:205], v[102:105]
	v_mfma_f32_16x16x32_bf16 v[94:97], v[162:165], v[202:205], v[94:97]
	v_mfma_f32_16x16x32_bf16 v[86:89], v[154:157], v[210:213], v[86:89]
	v_mfma_f32_16x16x32_bf16 v[78:81], v[162:165], v[210:213], v[78:81]
	v_mfma_f32_16x16x32_bf16 v[126:129], v[158:161], v[190:193], v[126:129]
	v_mfma_f32_16x16x32_bf16 v[122:125], v[166:169], v[190:193], v[122:125]
	v_mfma_f32_16x16x32_bf16 v[118:121], v[158:161], v[198:201], v[118:121]
	v_mfma_f32_16x16x32_bf16 v[110:113], v[166:169], v[198:201], v[110:113]
	v_mfma_f32_16x16x32_bf16 v[102:105], v[158:161], v[206:209], v[102:105]
	v_mfma_f32_16x16x32_bf16 v[94:97], v[166:169], v[206:209], v[94:97]
	v_mfma_f32_16x16x32_bf16 v[86:89], v[158:161], v[214:217], v[86:89]
	v_mfma_f32_16x16x32_bf16 v[78:81], v[166:169], v[214:217], v[78:81]
	v_mfma_f32_16x16x32_bf16 v[114:117], v[170:173], v[186:189], v[114:117]
	v_mfma_f32_16x16x32_bf16 v[106:109], v[178:181], v[186:189], v[106:109]
	v_mfma_f32_16x16x32_bf16 v[98:101], v[170:173], v[194:197], v[98:101]
	v_mfma_f32_16x16x32_bf16 v[90:93], v[178:181], v[194:197], v[90:93]
	v_mfma_f32_16x16x32_bf16 v[82:85], v[170:173], v[202:205], v[82:85]
	v_mfma_f32_16x16x32_bf16 v[74:77], v[178:181], v[202:205], v[74:77]
	v_mfma_f32_16x16x32_bf16 v[70:73], v[170:173], v[210:213], v[70:73]
	v_mfma_f32_16x16x32_bf16 v[66:69], v[178:181], v[210:213], v[66:69]
	v_mfma_f32_16x16x32_bf16 v[114:117], v[174:177], v[190:193], v[114:117]
	v_mfma_f32_16x16x32_bf16 v[106:109], v[182:185], v[190:193], v[106:109]
	v_mfma_f32_16x16x32_bf16 v[98:101], v[174:177], v[198:201], v[98:101]
	v_mfma_f32_16x16x32_bf16 v[90:93], v[182:185], v[198:201], v[90:93]
	v_mfma_f32_16x16x32_bf16 v[82:85], v[174:177], v[206:209], v[82:85]
	v_mfma_f32_16x16x32_bf16 v[74:77], v[182:185], v[206:209], v[74:77]
	v_mfma_f32_16x16x32_bf16 v[70:73], v[174:177], v[214:217], v[70:73]
	v_mfma_f32_16x16x32_bf16 v[66:69], v[182:185], v[214:217], v[66:69]
	s_setprio 0
	s_barrier
	s_add_i32 s44, s63, s49
	v_lshl_add_u64 v[146:147], s[52:53], 0, v[134:135]
	s_mov_b32 m0, s44
	ds_read_b128 v[186:189], v152 offset:16384
	ds_read_b128 v[190:193], v152 offset:17408
	ds_read_b128 v[194:197], v152 offset:18432
	ds_read_b128 v[198:201], v152 offset:19456
	ds_read_b128 v[202:205], v152 offset:20480
	ds_read_b128 v[206:209], v152 offset:21504
	ds_read_b128 v[210:213], v152 offset:22528
	ds_read_b128 v[214:217], v152 offset:23552
	global_load_lds_dwordx4 v[146:147], off
	s_add_i32 m0, s44, 0x2000
	s_add_u32 s76, s52, 0x100000
	v_lshl_add_u64 v[218:219], s[52:53], 0, v[130:131]
	s_addc_u32 s77, s53, 0
	s_add_i32 s44, s64, s49
	global_load_lds_dwordx4 v[218:219], off
	v_lshl_add_u64 v[220:221], s[76:77], 0, v[134:135]
	s_mov_b32 m0, s44
	v_lshl_add_u64 v[222:223], s[54:55], 0, v[132:133]
	global_load_lds_dwordx4 v[220:221], off
	v_lshl_add_u64 v[220:221], s[76:77], 0, v[130:131]
	s_add_i32 m0, s44, 0x2000
	s_nop 0
	global_load_lds_dwordx4 v[220:221], off
	v_lshl_add_u64 v[220:221], s[54:55], 0, v[136:137]
	s_mov_b32 m0, s43
	s_nop 0
	global_load_lds_dwordx4 v[220:221], off
	s_mov_b32 m0, s57
	s_nop 0
	global_load_lds_dwordx4 v[222:223], off
	s_waitcnt vmcnt(8)
	s_waitcnt lgkmcnt(0)
	s_barrier
	s_setprio 1
	s_waitcnt lgkmcnt(0)
	v_mfma_f32_16x16x32_bf16 v[62:65], v[154:157], v[186:189], v[62:65]
	v_mfma_f32_16x16x32_bf16 v[58:61], v[162:165], v[186:189], v[58:61]
	v_mfma_f32_16x16x32_bf16 v[54:57], v[154:157], v[194:197], v[54:57]
	v_mfma_f32_16x16x32_bf16 v[46:49], v[162:165], v[194:197], v[46:49]
	v_mfma_f32_16x16x32_bf16 v[38:41], v[154:157], v[202:205], v[38:41]
	v_mfma_f32_16x16x32_bf16 v[30:33], v[162:165], v[202:205], v[30:33]
	v_mfma_f32_16x16x32_bf16 v[22:25], v[154:157], v[210:213], v[22:25]
	v_mfma_f32_16x16x32_bf16 v[14:17], v[162:165], v[210:213], v[14:17]
	v_mfma_f32_16x16x32_bf16 v[62:65], v[158:161], v[190:193], v[62:65]
	v_mfma_f32_16x16x32_bf16 v[58:61], v[166:169], v[190:193], v[58:61]
	v_mfma_f32_16x16x32_bf16 v[54:57], v[158:161], v[198:201], v[54:57]
	v_mfma_f32_16x16x32_bf16 v[46:49], v[166:169], v[198:201], v[46:49]
	v_mfma_f32_16x16x32_bf16 v[38:41], v[158:161], v[206:209], v[38:41]
	v_mfma_f32_16x16x32_bf16 v[30:33], v[166:169], v[206:209], v[30:33]
	v_mfma_f32_16x16x32_bf16 v[22:25], v[158:161], v[214:217], v[22:25]
	v_mfma_f32_16x16x32_bf16 v[14:17], v[166:169], v[214:217], v[14:17]
	v_mfma_f32_16x16x32_bf16 v[50:53], v[170:173], v[186:189], v[50:53]
	v_mfma_f32_16x16x32_bf16 v[42:45], v[178:181], v[186:189], v[42:45]
	v_mfma_f32_16x16x32_bf16 v[34:37], v[170:173], v[194:197], v[34:37]
	v_mfma_f32_16x16x32_bf16 v[26:29], v[178:181], v[194:197], v[26:29]
	v_mfma_f32_16x16x32_bf16 v[18:21], v[170:173], v[202:205], v[18:21]
	v_mfma_f32_16x16x32_bf16 v[10:13], v[178:181], v[202:205], v[10:13]
	v_mfma_f32_16x16x32_bf16 v[6:9], v[170:173], v[210:213], v[6:9]
	v_mfma_f32_16x16x32_bf16 v[2:5], v[178:181], v[210:213], v[2:5]
	v_mfma_f32_16x16x32_bf16 v[50:53], v[174:177], v[190:193], v[50:53]
	v_mfma_f32_16x16x32_bf16 v[42:45], v[182:185], v[190:193], v[42:45]
	v_mfma_f32_16x16x32_bf16 v[34:37], v[174:177], v[198:201], v[34:37]
	v_mfma_f32_16x16x32_bf16 v[26:29], v[182:185], v[198:201], v[26:29]
	v_mfma_f32_16x16x32_bf16 v[18:21], v[174:177], v[206:209], v[18:21]
	v_mfma_f32_16x16x32_bf16 v[10:13], v[182:185], v[206:209], v[10:13]
	v_mfma_f32_16x16x32_bf16 v[6:9], v[174:177], v[214:217], v[6:9]
	v_mfma_f32_16x16x32_bf16 v[2:5], v[182:185], v[214:217], v[2:5]
	s_setprio 0
	s_barrier
	s_add_i32 s44, 0, 0x18000
	v_add_u32_e32 v153, s44, v148
	s_add_i32 s45, 0, 0x1c000
	ds_read_b128 v[154:157], v153
	ds_read_b128 v[158:161], v153 offset:1024
	ds_read_b128 v[162:165], v153 offset:2048
	ds_read_b128 v[166:169], v153 offset:3072
	v_add_u32_e32 v153, s45, v148
	ds_read_b128 v[170:173], v153
	ds_read_b128 v[174:177], v153 offset:1024
	ds_read_b128 v[178:181], v153 offset:2048
	ds_read_b128 v[182:185], v153 offset:3072
	s_add_u32 s54, s54, 0x100000
	s_addc_u32 s55, s55, 0
	s_mov_b32 m0, s58
	v_lshl_add_u64 v[224:225], s[54:55], 0, v[136:137]
	ds_read_b128 v[186:189], v152 offset:32768
	ds_read_b128 v[190:193], v152 offset:33792
	ds_read_b128 v[194:197], v152 offset:34816
	ds_read_b128 v[198:201], v152 offset:35840
	ds_read_b128 v[202:205], v152 offset:36864
	ds_read_b128 v[206:209], v152 offset:37888
	ds_read_b128 v[210:213], v152 offset:38912
	ds_read_b128 v[214:217], v152 offset:39936
	global_load_lds_dwordx4 v[224:225], off
	v_lshl_add_u64 v[224:225], s[54:55], 0, v[132:133]
	s_mov_b32 m0, s59
	s_nop 0
	global_load_lds_dwordx4 v[224:225], off
	s_waitcnt vmcnt(8)
	s_waitcnt lgkmcnt(0)
	s_barrier
	s_setprio 1
	s_waitcnt lgkmcnt(0)
	v_mfma_f32_16x16x32_bf16 v[126:129], v[154:157], v[186:189], v[126:129]
	v_mfma_f32_16x16x32_bf16 v[122:125], v[162:165], v[186:189], v[122:125]
	v_mfma_f32_16x16x32_bf16 v[118:121], v[154:157], v[194:197], v[118:121]
	v_mfma_f32_16x16x32_bf16 v[110:113], v[162:165], v[194:197], v[110:113]
	v_mfma_f32_16x16x32_bf16 v[102:105], v[154:157], v[202:205], v[102:105]
	v_mfma_f32_16x16x32_bf16 v[94:97], v[162:165], v[202:205], v[94:97]
	v_mfma_f32_16x16x32_bf16 v[86:89], v[154:157], v[210:213], v[86:89]
	v_mfma_f32_16x16x32_bf16 v[78:81], v[162:165], v[210:213], v[78:81]
	v_mfma_f32_16x16x32_bf16 v[126:129], v[158:161], v[190:193], v[126:129]
	v_mfma_f32_16x16x32_bf16 v[122:125], v[166:169], v[190:193], v[122:125]
	v_mfma_f32_16x16x32_bf16 v[118:121], v[158:161], v[198:201], v[118:121]
	v_mfma_f32_16x16x32_bf16 v[110:113], v[166:169], v[198:201], v[110:113]
	v_mfma_f32_16x16x32_bf16 v[102:105], v[158:161], v[206:209], v[102:105]
	v_mfma_f32_16x16x32_bf16 v[94:97], v[166:169], v[206:209], v[94:97]
	v_mfma_f32_16x16x32_bf16 v[86:89], v[158:161], v[214:217], v[86:89]
	v_mfma_f32_16x16x32_bf16 v[78:81], v[166:169], v[214:217], v[78:81]
	v_mfma_f32_16x16x32_bf16 v[114:117], v[170:173], v[186:189], v[114:117]
	v_mfma_f32_16x16x32_bf16 v[106:109], v[178:181], v[186:189], v[106:109]
	v_mfma_f32_16x16x32_bf16 v[98:101], v[170:173], v[194:197], v[98:101]
	v_mfma_f32_16x16x32_bf16 v[90:93], v[178:181], v[194:197], v[90:93]
	v_mfma_f32_16x16x32_bf16 v[82:85], v[170:173], v[202:205], v[82:85]
	v_mfma_f32_16x16x32_bf16 v[74:77], v[178:181], v[202:205], v[74:77]
	v_mfma_f32_16x16x32_bf16 v[70:73], v[170:173], v[210:213], v[70:73]
	v_mfma_f32_16x16x32_bf16 v[66:69], v[178:181], v[210:213], v[66:69]
	v_mfma_f32_16x16x32_bf16 v[114:117], v[174:177], v[190:193], v[114:117]
	v_mfma_f32_16x16x32_bf16 v[106:109], v[182:185], v[190:193], v[106:109]
	v_mfma_f32_16x16x32_bf16 v[98:101], v[174:177], v[198:201], v[98:101]
	v_mfma_f32_16x16x32_bf16 v[90:93], v[182:185], v[198:201], v[90:93]
	v_mfma_f32_16x16x32_bf16 v[82:85], v[174:177], v[206:209], v[82:85]
	v_mfma_f32_16x16x32_bf16 v[74:77], v[182:185], v[206:209], v[74:77]
	v_mfma_f32_16x16x32_bf16 v[70:73], v[174:177], v[214:217], v[70:73]
	v_mfma_f32_16x16x32_bf16 v[66:69], v[182:185], v[214:217], v[66:69]
	s_setprio 0
	s_barrier
	s_add_i32 s44, s44, s49
	v_lshl_add_u64 v[146:147], v[146:147], 0, s[14:15]
	s_mov_b32 m0, s44
	ds_read_b128 v[186:189], v152 offset:49152
	ds_read_b128 v[190:193], v152 offset:50176
	ds_read_b128 v[194:197], v152 offset:51200
	ds_read_b128 v[198:201], v152 offset:52224
	ds_read_b128 v[202:205], v152 offset:53248
	ds_read_b128 v[206:209], v152 offset:54272
	ds_read_b128 v[210:213], v152 offset:55296
	ds_read_b128 v[214:217], v152 offset:56320
	global_load_lds_dwordx4 v[146:147], off
	s_add_i32 m0, s44, 0x2000
	s_add_u32 s52, s52, 0x100080
	v_lshl_add_u64 v[146:147], v[218:219], 0, s[14:15]
	s_addc_u32 s53, s53, 0
	s_add_i32 s44, s45, s49
	global_load_lds_dwordx4 v[146:147], off
	v_lshl_add_u64 v[146:147], s[52:53], 0, v[134:135]
	s_mov_b32 m0, s44
	s_nop 0
	global_load_lds_dwordx4 v[146:147], off
	v_lshl_add_u64 v[146:147], s[52:53], 0, v[130:131]
	s_add_i32 m0, s44, 0x2000
	s_nop 0
	global_load_lds_dwordx4 v[146:147], off
	v_lshl_add_u64 v[146:147], v[220:221], 0, s[14:15]
	s_mov_b32 m0, s61
	s_nop 0
	global_load_lds_dwordx4 v[146:147], off
	v_lshl_add_u64 v[146:147], v[222:223], 0, s[14:15]
	s_mov_b32 m0, s62
	s_nop 0
	global_load_lds_dwordx4 v[146:147], off
	s_waitcnt vmcnt(8)
	s_waitcnt lgkmcnt(0)
	s_barrier
	s_setprio 1
	s_waitcnt lgkmcnt(0)
	v_mfma_f32_16x16x32_bf16 v[62:65], v[154:157], v[186:189], v[62:65]
	v_mfma_f32_16x16x32_bf16 v[58:61], v[162:165], v[186:189], v[58:61]
	v_mfma_f32_16x16x32_bf16 v[54:57], v[154:157], v[194:197], v[54:57]
	v_mfma_f32_16x16x32_bf16 v[46:49], v[162:165], v[194:197], v[46:49]
	v_mfma_f32_16x16x32_bf16 v[38:41], v[154:157], v[202:205], v[38:41]
	v_mfma_f32_16x16x32_bf16 v[30:33], v[162:165], v[202:205], v[30:33]
	v_mfma_f32_16x16x32_bf16 v[22:25], v[154:157], v[210:213], v[22:25]
	v_mfma_f32_16x16x32_bf16 v[14:17], v[162:165], v[210:213], v[14:17]
	v_mfma_f32_16x16x32_bf16 v[62:65], v[158:161], v[190:193], v[62:65]
	v_mfma_f32_16x16x32_bf16 v[58:61], v[166:169], v[190:193], v[58:61]
	v_mfma_f32_16x16x32_bf16 v[54:57], v[158:161], v[198:201], v[54:57]
	v_mfma_f32_16x16x32_bf16 v[46:49], v[166:169], v[198:201], v[46:49]
	v_mfma_f32_16x16x32_bf16 v[38:41], v[158:161], v[206:209], v[38:41]
	v_mfma_f32_16x16x32_bf16 v[30:33], v[166:169], v[206:209], v[30:33]
	v_mfma_f32_16x16x32_bf16 v[22:25], v[158:161], v[214:217], v[22:25]
	v_mfma_f32_16x16x32_bf16 v[14:17], v[166:169], v[214:217], v[14:17]
	v_mfma_f32_16x16x32_bf16 v[50:53], v[170:173], v[186:189], v[50:53]
	v_mfma_f32_16x16x32_bf16 v[42:45], v[178:181], v[186:189], v[42:45]
	v_mfma_f32_16x16x32_bf16 v[34:37], v[170:173], v[194:197], v[34:37]
	v_mfma_f32_16x16x32_bf16 v[26:29], v[178:181], v[194:197], v[26:29]
	v_mfma_f32_16x16x32_bf16 v[18:21], v[170:173], v[202:205], v[18:21]
	v_mfma_f32_16x16x32_bf16 v[10:13], v[178:181], v[202:205], v[10:13]
	v_mfma_f32_16x16x32_bf16 v[6:9], v[170:173], v[210:213], v[6:9]
	v_mfma_f32_16x16x32_bf16 v[2:5], v[178:181], v[210:213], v[2:5]
	v_mfma_f32_16x16x32_bf16 v[50:53], v[174:177], v[190:193], v[50:53]
	v_mfma_f32_16x16x32_bf16 v[42:45], v[182:185], v[190:193], v[42:45]
	v_mfma_f32_16x16x32_bf16 v[34:37], v[174:177], v[198:201], v[34:37]
	v_mfma_f32_16x16x32_bf16 v[26:29], v[182:185], v[198:201], v[26:29]
	v_mfma_f32_16x16x32_bf16 v[18:21], v[174:177], v[206:209], v[18:21]
	v_mfma_f32_16x16x32_bf16 v[10:13], v[182:185], v[206:209], v[10:13]
	v_mfma_f32_16x16x32_bf16 v[6:9], v[174:177], v[214:217], v[6:9]
	v_mfma_f32_16x16x32_bf16 v[2:5], v[182:185], v[214:217], v[2:5]
	s_setprio 0
	s_barrier
	s_add_i32 s74, s74, 2
	s_add_u32 s50, s50, 0x100
	s_addc_u32 s51, s51, 0
	s_add_u32 s72, s72, 0x100
	s_addc_u32 s73, s73, 0
	s_cmp_lt_u32 s74, 62
	s_cbranch_scc1 .LBB0_290
	s_andn2_b64 vcc, exec, s[16:17]
	s_cbranch_vccnz .LBB0_293
	s_barrier

.LBB0_317:
	ds_read_b128 v[18:21], v190
	ds_read_b128 v[22:25], v190 offset:1024
	ds_read_b128 v[26:29], v190 offset:2048
	ds_read_b128 v[30:33], v190 offset:3072
	ds_read_b128 v[2:5], v191
	ds_read_b128 v[6:9], v191 offset:1024
	ds_read_b128 v[10:13], v191 offset:2048
	ds_read_b128 v[14:17], v191 offset:3072
	s_add_u32 s44, s54, 0xfff80080
	s_addc_u32 s45, s55, -1
	s_cmp_eq_u32 s74, 28
	s_cselect_b32 s59, s37, s45
	s_cselect_b32 s58, s53, s44
	s_cselect_b32 s57, s39, s73
	s_cselect_b32 s56, s71, s72
	v_lshl_add_u64 v[220:221], s[54:55], 0, v[172:173]
	s_add_i32 m0, s49, 0xc000
	ds_read_b128 v[180:183], v192
	ds_read_b128 v[184:187], v192 offset:1024
	ds_read_b128 v[196:199], v192 offset:2048
	ds_read_b128 v[200:203], v192 offset:3072
	ds_read_b128 v[204:207], v192 offset:4096
	ds_read_b128 v[208:211], v192 offset:5120
	ds_read_b128 v[212:215], v192 offset:6144
	ds_read_b128 v[216:219], v192 offset:7168
	global_load_lds_dwordx4 v[220:221], off
	v_lshl_add_u64 v[220:221], s[54:55], 0, v[174:175]
	s_add_i32 m0, s49, 0xe000
	s_nop 0
	global_load_lds_dwordx4 v[220:221], off
	s_waitcnt vmcnt(8)
	s_waitcnt lgkmcnt(0)
	s_barrier
	s_setprio 1
	s_waitcnt lgkmcnt(0)
	s_nop 1
	v_mfma_scale_f32_16x16x128_f8f6f4 v[158:161], v[18:25], v[180:187], v[158:161], v193, v193 op_sel_hi:[0,0,0]
	s_nop 1
	v_mfma_scale_f32_16x16x128_f8f6f4 v[154:157], v[26:33], v[180:187], v[154:157], v193, v193 op_sel_hi:[0,0,0]
	s_nop 1
	v_mfma_scale_f32_16x16x128_f8f6f4 v[142:145], v[18:25], v[196:203], v[142:145], v193, v193 op_sel_hi:[0,0,0]
	s_nop 1
	v_mfma_scale_f32_16x16x128_f8f6f4 v[138:141], v[26:33], v[196:203], v[138:141], v193, v193 op_sel_hi:[0,0,0]
	s_nop 1
	v_mfma_scale_f32_16x16x128_f8f6f4 v[126:129], v[18:25], v[204:211], v[126:129], v193, v193 op_sel_hi:[0,0,0]
	s_nop 1
	v_mfma_scale_f32_16x16x128_f8f6f4 v[122:125], v[26:33], v[204:211], v[122:125], v193, v193 op_sel_hi:[0,0,0]
	s_nop 1
	v_mfma_scale_f32_16x16x128_f8f6f4 v[110:113], v[18:25], v[212:219], v[110:113], v193, v193 op_sel_hi:[0,0,0]
	s_nop 1
	v_mfma_scale_f32_16x16x128_f8f6f4 v[106:109], v[26:33], v[212:219], v[106:109], v193, v193 op_sel_hi:[0,0,0]
	s_nop 1
	v_mfma_scale_f32_16x16x128_f8f6f4 v[150:153], v[2:9], v[180:187], v[150:153], v193, v193 op_sel_hi:[0,0,0]
	s_nop 1
	v_mfma_scale_f32_16x16x128_f8f6f4 v[146:149], v[10:17], v[180:187], v[146:149], v193, v193 op_sel_hi:[0,0,0]
	s_nop 1
	v_mfma_scale_f32_16x16x128_f8f6f4 v[134:137], v[2:9], v[196:203], v[134:137], v193, v193 op_sel_hi:[0,0,0]
	s_nop 1
	v_mfma_scale_f32_16x16x128_f8f6f4 v[130:133], v[10:17], v[196:203], v[130:133], v193, v193 op_sel_hi:[0,0,0]
	s_nop 1
	v_mfma_scale_f32_16x16x128_f8f6f4 v[118:121], v[2:9], v[204:211], v[118:121], v193, v193 op_sel_hi:[0,0,0]
	s_nop 1
	v_mfma_scale_f32_16x16x128_f8f6f4 v[114:117], v[10:17], v[204:211], v[114:117], v193, v193 op_sel_hi:[0,0,0]
	s_nop 1
	v_mfma_scale_f32_16x16x128_f8f6f4 v[102:105], v[2:9], v[212:219], v[102:105], v193, v193 op_sel_hi:[0,0,0]
	s_nop 1
	v_mfma_scale_f32_16x16x128_f8f6f4 v[98:101], v[10:17], v[212:219], v[98:101], v193, v193 op_sel_hi:[0,0,0]
	s_setprio 0
	s_barrier
	s_add_i32 s44, s66, s47
	v_lshl_add_u64 v[180:181], s[56:57], 0, v[164:165]
	s_mov_b32 m0, s44
	ds_read_b128 v[196:199], v192 offset:16384
	ds_read_b128 v[200:203], v192 offset:17408
	ds_read_b128 v[204:207], v192 offset:18432
	ds_read_b128 v[208:211], v192 offset:19456
	ds_read_b128 v[212:215], v192 offset:20480
	ds_read_b128 v[216:219], v192 offset:21504
	ds_read_b128 v[220:223], v192 offset:22528
	ds_read_b128 v[224:227], v192 offset:23552
	global_load_lds_dwordx4 v[180:181], off
	s_add_i32 m0, s44, 0x2000
	s_add_u32 s76, s56, 0x80000
	v_lshl_add_u64 v[182:183], s[56:57], 0, v[168:169]
	s_addc_u32 s77, s57, 0
	s_add_i32 s44, s67, s47
	global_load_lds_dwordx4 v[182:183], off
	v_lshl_add_u64 v[184:185], s[76:77], 0, v[164:165]
	s_mov_b32 m0, s44
	v_lshl_add_u64 v[186:187], s[58:59], 0, v[166:167]
	global_load_lds_dwordx4 v[184:185], off
	v_lshl_add_u64 v[184:185], s[76:77], 0, v[168:169]
	s_add_i32 m0, s44, 0x2000
	s_nop 0
	global_load_lds_dwordx4 v[184:185], off
	v_lshl_add_u64 v[184:185], s[58:59], 0, v[162:163]
	s_mov_b32 m0, s49
	s_nop 0
	global_load_lds_dwordx4 v[184:185], off
	s_mov_b32 m0, s51
	s_nop 0
	global_load_lds_dwordx4 v[186:187], off
	s_waitcnt vmcnt(8)
	s_waitcnt lgkmcnt(0)
	s_barrier
	s_setprio 1
	s_waitcnt lgkmcnt(0)
	s_nop 1
	v_mfma_scale_f32_16x16x128_f8f6f4 v[94:97], v[18:25], v[196:203], v[94:97], v193, v193 op_sel_hi:[0,0,0]
	s_nop 1
	v_mfma_scale_f32_16x16x128_f8f6f4 v[90:93], v[26:33], v[196:203], v[90:93], v193, v193 op_sel_hi:[0,0,0]
	s_nop 1
	v_mfma_scale_f32_16x16x128_f8f6f4 v[78:81], v[18:25], v[204:211], v[78:81], v193, v193 op_sel_hi:[0,0,0]
	s_nop 1
	v_mfma_scale_f32_16x16x128_f8f6f4 v[74:77], v[26:33], v[204:211], v[74:77], v193, v193 op_sel_hi:[0,0,0]
	s_nop 1
	v_mfma_scale_f32_16x16x128_f8f6f4 v[62:65], v[18:25], v[212:219], v[62:65], v193, v193 op_sel_hi:[0,0,0]
	s_nop 1
	v_mfma_scale_f32_16x16x128_f8f6f4 v[58:61], v[26:33], v[212:219], v[58:61], v193, v193 op_sel_hi:[0,0,0]
	s_nop 1
	v_mfma_scale_f32_16x16x128_f8f6f4 v[46:49], v[18:25], v[220:227], v[46:49], v193, v193 op_sel_hi:[0,0,0]
	s_nop 1
	v_mfma_scale_f32_16x16x128_f8f6f4 v[42:45], v[26:33], v[220:227], v[42:45], v193, v193 op_sel_hi:[0,0,0]
	s_nop 1
	v_mfma_scale_f32_16x16x128_f8f6f4 v[86:89], v[2:9], v[196:203], v[86:89], v193, v193 op_sel_hi:[0,0,0]
	s_nop 1
	v_mfma_scale_f32_16x16x128_f8f6f4 v[82:85], v[10:17], v[196:203], v[82:85], v193, v193 op_sel_hi:[0,0,0]
	s_nop 1
	v_mfma_scale_f32_16x16x128_f8f6f4 v[70:73], v[2:9], v[204:211], v[70:73], v193, v193 op_sel_hi:[0,0,0]
	s_nop 1
	v_mfma_scale_f32_16x16x128_f8f6f4 v[66:69], v[10:17], v[204:211], v[66:69], v193, v193 op_sel_hi:[0,0,0]
	s_nop 1
	v_mfma_scale_f32_16x16x128_f8f6f4 v[54:57], v[2:9], v[212:219], v[54:57], v193, v193 op_sel_hi:[0,0,0]
	s_nop 1
	v_mfma_scale_f32_16x16x128_f8f6f4 v[50:53], v[10:17], v[212:219], v[50:53], v193, v193 op_sel_hi:[0,0,0]
	s_nop 1
	v_mfma_scale_f32_16x16x128_f8f6f4 v[38:41], v[2:9], v[220:227], v[38:41], v193, v193 op_sel_hi:[0,0,0]
	s_nop 1
	v_mfma_scale_f32_16x16x128_f8f6f4 v[34:37], v[10:17], v[220:227], v[34:37], v193, v193 op_sel_hi:[0,0,0]
	s_setprio 0
	s_barrier
	s_add_i32 s44, 0, 0x18000
	s_add_i32 s45, 0, 0x1c000
	v_add_u32_e32 v14, s44, v188
	v_add_u32_e32 v30, s45, v188
	ds_read_b128 v[2:5], v14
	ds_read_b128 v[6:9], v14 offset:1024
	ds_read_b128 v[10:13], v14 offset:2048
	ds_read_b128 v[14:17], v14 offset:3072
	ds_read_b128 v[18:21], v30
	ds_read_b128 v[22:25], v30 offset:1024
	ds_read_b128 v[26:29], v30 offset:2048
	ds_read_b128 v[30:33], v30 offset:3072
	s_add_u32 s58, s58, 0x80000
	s_addc_u32 s59, s59, 0
	s_mov_b32 m0, s60
	v_lshl_add_u64 v[228:229], s[58:59], 0, v[162:163]
	ds_read_b128 v[196:199], v192 offset:32768
	ds_read_b128 v[200:203], v192 offset:33792
	ds_read_b128 v[204:207], v192 offset:34816
	ds_read_b128 v[208:211], v192 offset:35840
	ds_read_b128 v[212:215], v192 offset:36864
	ds_read_b128 v[216:219], v192 offset:37888
	ds_read_b128 v[220:223], v192 offset:38912
	ds_read_b128 v[224:227], v192 offset:39936
	global_load_lds_dwordx4 v[228:229], off
	v_lshl_add_u64 v[228:229], s[58:59], 0, v[166:167]
	s_mov_b32 m0, s61
	s_nop 0
	global_load_lds_dwordx4 v[228:229], off
	s_waitcnt vmcnt(8)
	s_waitcnt lgkmcnt(0)
	s_barrier
	s_setprio 1
	s_waitcnt lgkmcnt(0)
	s_nop 1
	v_mfma_scale_f32_16x16x128_f8f6f4 v[158:161], v[2:9], v[196:203], v[158:161], v193, v193 op_sel_hi:[0,0,0]
	s_nop 1
	v_mfma_scale_f32_16x16x128_f8f6f4 v[154:157], v[10:17], v[196:203], v[154:157], v193, v193 op_sel_hi:[0,0,0]
	s_nop 1
	v_mfma_scale_f32_16x16x128_f8f6f4 v[142:145], v[2:9], v[204:211], v[142:145], v193, v193 op_sel_hi:[0,0,0]
	s_nop 1
	v_mfma_scale_f32_16x16x128_f8f6f4 v[138:141], v[10:17], v[204:211], v[138:141], v193, v193 op_sel_hi:[0,0,0]
	s_nop 1
	v_mfma_scale_f32_16x16x128_f8f6f4 v[126:129], v[2:9], v[212:219], v[126:129], v193, v193 op_sel_hi:[0,0,0]
	s_nop 1
	v_mfma_scale_f32_16x16x128_f8f6f4 v[122:125], v[10:17], v[212:219], v[122:125], v193, v193 op_sel_hi:[0,0,0]
	s_nop 1
	v_mfma_scale_f32_16x16x128_f8f6f4 v[110:113], v[2:9], v[220:227], v[110:113], v193, v193 op_sel_hi:[0,0,0]
	s_nop 1
	v_mfma_scale_f32_16x16x128_f8f6f4 v[106:109], v[10:17], v[220:227], v[106:109], v193, v193 op_sel_hi:[0,0,0]
	s_nop 1
	v_mfma_scale_f32_16x16x128_f8f6f4 v[150:153], v[18:25], v[196:203], v[150:153], v193, v193 op_sel_hi:[0,0,0]
	s_nop 1
	v_mfma_scale_f32_16x16x128_f8f6f4 v[146:149], v[26:33], v[196:203], v[146:149], v193, v193 op_sel_hi:[0,0,0]
	s_nop 1
	v_mfma_scale_f32_16x16x128_f8f6f4 v[134:137], v[18:25], v[204:211], v[134:137], v193, v193 op_sel_hi:[0,0,0]
	s_nop 1
	v_mfma_scale_f32_16x16x128_f8f6f4 v[130:133], v[26:33], v[204:211], v[130:133], v193, v193 op_sel_hi:[0,0,0]
	s_nop 1
	v_mfma_scale_f32_16x16x128_f8f6f4 v[118:121], v[18:25], v[212:219], v[118:121], v193, v193 op_sel_hi:[0,0,0]
	s_nop 1
	v_mfma_scale_f32_16x16x128_f8f6f4 v[114:117], v[26:33], v[212:219], v[114:117], v193, v193 op_sel_hi:[0,0,0]
	s_nop 1
	v_mfma_scale_f32_16x16x128_f8f6f4 v[102:105], v[18:25], v[220:227], v[102:105], v193, v193 op_sel_hi:[0,0,0]
	s_nop 1
	v_mfma_scale_f32_16x16x128_f8f6f4 v[98:101], v[26:33], v[220:227], v[98:101], v193, v193 op_sel_hi:[0,0,0]
	s_setprio 0
	s_barrier
	s_add_i32 s44, s44, s47
	v_lshl_add_u64 v[180:181], v[180:181], 0, s[12:13]
	s_mov_b32 m0, s44
	ds_read_b128 v[196:199], v192 offset:49152
	ds_read_b128 v[200:203], v192 offset:50176
	ds_read_b128 v[204:207], v192 offset:51200
	ds_read_b128 v[208:211], v192 offset:52224
	ds_read_b128 v[212:215], v192 offset:53248
	ds_read_b128 v[216:219], v192 offset:54272
	ds_read_b128 v[220:223], v192 offset:55296
	ds_read_b128 v[224:227], v192 offset:56320
	global_load_lds_dwordx4 v[180:181], off
	s_add_i32 m0, s44, 0x2000
	s_add_u32 s56, s56, 0x80080
	v_lshl_add_u64 v[180:181], v[182:183], 0, s[12:13]
	s_addc_u32 s57, s57, 0
	s_add_i32 s44, s45, s47
	global_load_lds_dwordx4 v[180:181], off
	v_lshl_add_u64 v[180:181], s[56:57], 0, v[164:165]
	s_mov_b32 m0, s44
	s_nop 0
	global_load_lds_dwordx4 v[180:181], off
	v_lshl_add_u64 v[180:181], s[56:57], 0, v[168:169]
	s_add_i32 m0, s44, 0x2000
	s_nop 0
	global_load_lds_dwordx4 v[180:181], off
	v_lshl_add_u64 v[180:181], v[184:185], 0, s[12:13]
	s_mov_b32 m0, s63
	s_nop 0
	global_load_lds_dwordx4 v[180:181], off
	v_lshl_add_u64 v[180:181], v[186:187], 0, s[12:13]
	s_mov_b32 m0, s64
	s_nop 0
	global_load_lds_dwordx4 v[180:181], off
	s_waitcnt vmcnt(8)
	s_waitcnt lgkmcnt(0)
	s_barrier
	s_setprio 1
	s_waitcnt lgkmcnt(0)
	s_nop 1
	v_mfma_scale_f32_16x16x128_f8f6f4 v[94:97], v[2:9], v[196:203], v[94:97], v193, v193 op_sel_hi:[0,0,0]
	s_nop 1
	v_mfma_scale_f32_16x16x128_f8f6f4 v[90:93], v[10:17], v[196:203], v[90:93], v193, v193 op_sel_hi:[0,0,0]
	s_nop 1
	v_mfma_scale_f32_16x16x128_f8f6f4 v[78:81], v[2:9], v[204:211], v[78:81], v193, v193 op_sel_hi:[0,0,0]
	s_nop 1
	v_mfma_scale_f32_16x16x128_f8f6f4 v[74:77], v[10:17], v[204:211], v[74:77], v193, v193 op_sel_hi:[0,0,0]
	s_nop 1
	v_mfma_scale_f32_16x16x128_f8f6f4 v[62:65], v[2:9], v[212:219], v[62:65], v193, v193 op_sel_hi:[0,0,0]
	s_nop 1
	v_mfma_scale_f32_16x16x128_f8f6f4 v[58:61], v[10:17], v[212:219], v[58:61], v193, v193 op_sel_hi:[0,0,0]
	s_nop 1
	v_mfma_scale_f32_16x16x128_f8f6f4 v[46:49], v[2:9], v[220:227], v[46:49], v193, v193 op_sel_hi:[0,0,0]
	s_nop 1
	v_mfma_scale_f32_16x16x128_f8f6f4 v[42:45], v[10:17], v[220:227], v[42:45], v193, v193 op_sel_hi:[0,0,0]
	s_nop 1
	v_mfma_scale_f32_16x16x128_f8f6f4 v[86:89], v[18:25], v[196:203], v[86:89], v193, v193 op_sel_hi:[0,0,0]
	s_nop 1
	v_mfma_scale_f32_16x16x128_f8f6f4 v[82:85], v[26:33], v[196:203], v[82:85], v193, v193 op_sel_hi:[0,0,0]
	s_nop 1
	v_mfma_scale_f32_16x16x128_f8f6f4 v[70:73], v[18:25], v[204:211], v[70:73], v193, v193 op_sel_hi:[0,0,0]
	s_nop 1
	v_mfma_scale_f32_16x16x128_f8f6f4 v[66:69], v[26:33], v[204:211], v[66:69], v193, v193 op_sel_hi:[0,0,0]
	s_nop 1
	v_mfma_scale_f32_16x16x128_f8f6f4 v[54:57], v[18:25], v[212:219], v[54:57], v193, v193 op_sel_hi:[0,0,0]
	s_nop 1
	v_mfma_scale_f32_16x16x128_f8f6f4 v[50:53], v[26:33], v[212:219], v[50:53], v193, v193 op_sel_hi:[0,0,0]
	s_nop 1
	v_mfma_scale_f32_16x16x128_f8f6f4 v[38:41], v[18:25], v[220:227], v[38:41], v193, v193 op_sel_hi:[0,0,0]
	s_nop 1
	v_mfma_scale_f32_16x16x128_f8f6f4 v[34:37], v[26:33], v[220:227], v[34:37], v193, v193 op_sel_hi:[0,0,0]
	s_setprio 0
	s_barrier
	s_add_i32 s74, s74, 2
	s_add_u32 s54, s54, 0x100
	s_addc_u32 s55, s55, 0
	s_add_u32 s72, s72, 0x100
	s_addc_u32 s73, s73, 0
	s_cmp_lt_u32 s74, 30
	s_cbranch_scc1 .LBB0_317
	s_nop 15
	s_nop 15
	s_andn2_b64 vcc, exec, s[14:15]
	s_cbranch_vccnz .LBB0_322
	s_barrier
	v_lshl_add_u32 v2, s52, 8, v1
	s_cmp_gt_i32 s50, 5
	s_mov_b64 s[52:53], -1
	s_cbranch_scc1 .LBB0_323

.LBB0_394:
	ds_read_b128 v[18:21], v189
	ds_read_b128 v[22:25], v189 offset:1024
	ds_read_b128 v[26:29], v189 offset:2048
	ds_read_b128 v[30:33], v189 offset:3072
	ds_read_b128 v[2:5], v190
	ds_read_b128 v[6:9], v190 offset:1024
	ds_read_b128 v[10:13], v190 offset:2048
	ds_read_b128 v[14:17], v190 offset:3072
	s_add_u32 s42, s40, 0xfffe0080
	s_addc_u32 s43, s41, -1
	s_cmp_eq_u32 s68, 4
	s_cselect_b32 s51, s25, s43
	s_cselect_b32 s50, s64, s42
	s_cselect_b32 s43, s23, s67
	s_cselect_b32 s42, s65, s66
	v_lshl_add_u64 v[218:219], s[40:41], 0, v[170:171]
	s_add_i32 m0, s39, 0xc000
	ds_read_b128 v[178:181], v191
	ds_read_b128 v[182:185], v191 offset:1024
	ds_read_b128 v[194:197], v191 offset:2048
	ds_read_b128 v[198:201], v191 offset:3072
	ds_read_b128 v[202:205], v191 offset:4096
	ds_read_b128 v[206:209], v191 offset:5120
	ds_read_b128 v[210:213], v191 offset:6144
	ds_read_b128 v[214:217], v191 offset:7168
	global_load_lds_dwordx4 v[218:219], off
	v_lshl_add_u64 v[218:219], s[40:41], 0, v[172:173]
	s_add_i32 m0, s39, 0xe000
	s_nop 0
	global_load_lds_dwordx4 v[218:219], off
	s_waitcnt vmcnt(8)
	s_waitcnt lgkmcnt(0)
	s_barrier
	s_setprio 1
	s_waitcnt lgkmcnt(0)
	s_nop 1
	v_mfma_scale_f32_16x16x128_f8f6f4 v[158:161], v[18:25], v[178:185], v[158:161], v192, v192 op_sel_hi:[0,0,0]
	s_nop 1
	v_mfma_scale_f32_16x16x128_f8f6f4 v[154:157], v[26:33], v[178:185], v[154:157], v192, v192 op_sel_hi:[0,0,0]
	s_nop 1
	v_mfma_scale_f32_16x16x128_f8f6f4 v[142:145], v[18:25], v[194:201], v[142:145], v192, v192 op_sel_hi:[0,0,0]
	s_nop 1
	v_mfma_scale_f32_16x16x128_f8f6f4 v[138:141], v[26:33], v[194:201], v[138:141], v192, v192 op_sel_hi:[0,0,0]
	s_nop 1
	v_mfma_scale_f32_16x16x128_f8f6f4 v[126:129], v[18:25], v[202:209], v[126:129], v192, v192 op_sel_hi:[0,0,0]
	s_nop 1
	v_mfma_scale_f32_16x16x128_f8f6f4 v[122:125], v[26:33], v[202:209], v[122:125], v192, v192 op_sel_hi:[0,0,0]
	s_nop 1
	v_mfma_scale_f32_16x16x128_f8f6f4 v[110:113], v[18:25], v[210:217], v[110:113], v192, v192 op_sel_hi:[0,0,0]
	s_nop 1
	v_mfma_scale_f32_16x16x128_f8f6f4 v[106:109], v[26:33], v[210:217], v[106:109], v192, v192 op_sel_hi:[0,0,0]
	s_nop 1
	v_mfma_scale_f32_16x16x128_f8f6f4 v[150:153], v[2:9], v[178:185], v[150:153], v192, v192 op_sel_hi:[0,0,0]
	s_nop 1
	v_mfma_scale_f32_16x16x128_f8f6f4 v[146:149], v[10:17], v[178:185], v[146:149], v192, v192 op_sel_hi:[0,0,0]
	s_nop 1
	v_mfma_scale_f32_16x16x128_f8f6f4 v[134:137], v[2:9], v[194:201], v[134:137], v192, v192 op_sel_hi:[0,0,0]
	s_nop 1
	v_mfma_scale_f32_16x16x128_f8f6f4 v[130:133], v[10:17], v[194:201], v[130:133], v192, v192 op_sel_hi:[0,0,0]
	s_nop 1
	v_mfma_scale_f32_16x16x128_f8f6f4 v[118:121], v[2:9], v[202:209], v[118:121], v192, v192 op_sel_hi:[0,0,0]
	s_nop 1
	v_mfma_scale_f32_16x16x128_f8f6f4 v[114:117], v[10:17], v[202:209], v[114:117], v192, v192 op_sel_hi:[0,0,0]
	s_nop 1
	v_mfma_scale_f32_16x16x128_f8f6f4 v[102:105], v[2:9], v[210:217], v[102:105], v192, v192 op_sel_hi:[0,0,0]
	s_nop 1
	v_mfma_scale_f32_16x16x128_f8f6f4 v[98:101], v[10:17], v[210:217], v[98:101], v192, v192 op_sel_hi:[0,0,0]
	s_setprio 0
	s_barrier
	s_add_i32 s44, s59, s49
	v_lshl_add_u64 v[178:179], s[42:43], 0, v[166:167]
	s_mov_b32 m0, s44
	ds_read_b128 v[194:197], v191 offset:16384
	ds_read_b128 v[198:201], v191 offset:17408
	ds_read_b128 v[202:205], v191 offset:18432
	ds_read_b128 v[206:209], v191 offset:19456
	ds_read_b128 v[210:213], v191 offset:20480
	ds_read_b128 v[214:217], v191 offset:21504
	ds_read_b128 v[218:221], v191 offset:22528
	ds_read_b128 v[222:225], v191 offset:23552
	global_load_lds_dwordx4 v[178:179], off
	s_add_i32 m0, s44, 0x2000
	s_add_u32 s70, s42, 0x20000
	v_lshl_add_u64 v[180:181], s[42:43], 0, v[162:163]
	s_addc_u32 s71, s43, 0
	s_add_i32 s44, s60, s49
	global_load_lds_dwordx4 v[180:181], off
	v_lshl_add_u64 v[182:183], s[70:71], 0, v[166:167]
	s_mov_b32 m0, s44
	v_lshl_add_u64 v[184:185], s[50:51], 0, v[164:165]
	global_load_lds_dwordx4 v[182:183], off
	v_lshl_add_u64 v[182:183], s[70:71], 0, v[162:163]
	s_add_i32 m0, s44, 0x2000
	s_nop 0
	global_load_lds_dwordx4 v[182:183], off
	v_lshl_add_u64 v[182:183], s[50:51], 0, v[168:169]
	s_mov_b32 m0, s39
	s_nop 0
	global_load_lds_dwordx4 v[182:183], off
	s_mov_b32 m0, s53
	s_nop 0
	global_load_lds_dwordx4 v[184:185], off
	s_waitcnt vmcnt(8)
	s_waitcnt lgkmcnt(0)
	s_barrier
	s_setprio 1
	s_waitcnt lgkmcnt(0)
	s_nop 1
	v_mfma_scale_f32_16x16x128_f8f6f4 v[94:97], v[18:25], v[194:201], v[94:97], v192, v192 op_sel_hi:[0,0,0]
	s_nop 1
	v_mfma_scale_f32_16x16x128_f8f6f4 v[90:93], v[26:33], v[194:201], v[90:93], v192, v192 op_sel_hi:[0,0,0]
	s_nop 1
	v_mfma_scale_f32_16x16x128_f8f6f4 v[78:81], v[18:25], v[202:209], v[78:81], v192, v192 op_sel_hi:[0,0,0]
	s_nop 1
	v_mfma_scale_f32_16x16x128_f8f6f4 v[74:77], v[26:33], v[202:209], v[74:77], v192, v192 op_sel_hi:[0,0,0]
	s_nop 1
	v_mfma_scale_f32_16x16x128_f8f6f4 v[62:65], v[18:25], v[210:217], v[62:65], v192, v192 op_sel_hi:[0,0,0]
	s_nop 1
	v_mfma_scale_f32_16x16x128_f8f6f4 v[58:61], v[26:33], v[210:217], v[58:61], v192, v192 op_sel_hi:[0,0,0]
	s_nop 1
	v_mfma_scale_f32_16x16x128_f8f6f4 v[46:49], v[18:25], v[218:225], v[46:49], v192, v192 op_sel_hi:[0,0,0]
	s_nop 1
	v_mfma_scale_f32_16x16x128_f8f6f4 v[42:45], v[26:33], v[218:225], v[42:45], v192, v192 op_sel_hi:[0,0,0]
	s_nop 1
	v_mfma_scale_f32_16x16x128_f8f6f4 v[86:89], v[2:9], v[194:201], v[86:89], v192, v192 op_sel_hi:[0,0,0]
	s_nop 1
	v_mfma_scale_f32_16x16x128_f8f6f4 v[82:85], v[10:17], v[194:201], v[82:85], v192, v192 op_sel_hi:[0,0,0]
	s_nop 1
	v_mfma_scale_f32_16x16x128_f8f6f4 v[70:73], v[2:9], v[202:209], v[70:73], v192, v192 op_sel_hi:[0,0,0]
	s_nop 1
	v_mfma_scale_f32_16x16x128_f8f6f4 v[66:69], v[10:17], v[202:209], v[66:69], v192, v192 op_sel_hi:[0,0,0]
	s_nop 1
	v_mfma_scale_f32_16x16x128_f8f6f4 v[54:57], v[2:9], v[210:217], v[54:57], v192, v192 op_sel_hi:[0,0,0]
	s_nop 1
	v_mfma_scale_f32_16x16x128_f8f6f4 v[50:53], v[10:17], v[210:217], v[50:53], v192, v192 op_sel_hi:[0,0,0]
	s_nop 1
	v_mfma_scale_f32_16x16x128_f8f6f4 v[38:41], v[2:9], v[218:225], v[38:41], v192, v192 op_sel_hi:[0,0,0]
	s_nop 1
	v_mfma_scale_f32_16x16x128_f8f6f4 v[34:37], v[10:17], v[218:225], v[34:37], v192, v192 op_sel_hi:[0,0,0]
	s_setprio 0
	s_barrier
	s_add_i32 s44, 0, 0x18000
	s_add_i32 s45, 0, 0x1c000
	v_add_u32_e32 v14, s44, v187
	v_add_u32_e32 v30, s45, v187
	ds_read_b128 v[2:5], v14
	ds_read_b128 v[6:9], v14 offset:1024
	ds_read_b128 v[10:13], v14 offset:2048
	ds_read_b128 v[14:17], v14 offset:3072
	ds_read_b128 v[18:21], v30
	ds_read_b128 v[22:25], v30 offset:1024
	ds_read_b128 v[26:29], v30 offset:2048
	ds_read_b128 v[30:33], v30 offset:3072
	s_add_u32 s50, s50, 0x20000
	s_addc_u32 s51, s51, 0
	s_mov_b32 m0, s54
	v_lshl_add_u64 v[226:227], s[50:51], 0, v[168:169]
	ds_read_b128 v[194:197], v191 offset:32768
	ds_read_b128 v[198:201], v191 offset:33792
	ds_read_b128 v[202:205], v191 offset:34816
	ds_read_b128 v[206:209], v191 offset:35840
	ds_read_b128 v[210:213], v191 offset:36864
	ds_read_b128 v[214:217], v191 offset:37888
	ds_read_b128 v[218:221], v191 offset:38912
	ds_read_b128 v[222:225], v191 offset:39936
	global_load_lds_dwordx4 v[226:227], off
	v_lshl_add_u64 v[226:227], s[50:51], 0, v[164:165]
	s_mov_b32 m0, s55
	s_nop 0
	global_load_lds_dwordx4 v[226:227], off
	s_waitcnt vmcnt(8)
	s_waitcnt lgkmcnt(0)
	s_barrier
	s_setprio 1
	s_waitcnt lgkmcnt(0)
	s_nop 1
	v_mfma_scale_f32_16x16x128_f8f6f4 v[158:161], v[2:9], v[194:201], v[158:161], v192, v192 op_sel_hi:[0,0,0]
	s_nop 1
	v_mfma_scale_f32_16x16x128_f8f6f4 v[154:157], v[10:17], v[194:201], v[154:157], v192, v192 op_sel_hi:[0,0,0]
	s_nop 1
	v_mfma_scale_f32_16x16x128_f8f6f4 v[142:145], v[2:9], v[202:209], v[142:145], v192, v192 op_sel_hi:[0,0,0]
	s_nop 1
	v_mfma_scale_f32_16x16x128_f8f6f4 v[138:141], v[10:17], v[202:209], v[138:141], v192, v192 op_sel_hi:[0,0,0]
	s_nop 1
	v_mfma_scale_f32_16x16x128_f8f6f4 v[126:129], v[2:9], v[210:217], v[126:129], v192, v192 op_sel_hi:[0,0,0]
	s_nop 1
	v_mfma_scale_f32_16x16x128_f8f6f4 v[122:125], v[10:17], v[210:217], v[122:125], v192, v192 op_sel_hi:[0,0,0]
	s_nop 1
	v_mfma_scale_f32_16x16x128_f8f6f4 v[110:113], v[2:9], v[218:225], v[110:113], v192, v192 op_sel_hi:[0,0,0]
	s_nop 1
	v_mfma_scale_f32_16x16x128_f8f6f4 v[106:109], v[10:17], v[218:225], v[106:109], v192, v192 op_sel_hi:[0,0,0]
	s_nop 1
	v_mfma_scale_f32_16x16x128_f8f6f4 v[150:153], v[18:25], v[194:201], v[150:153], v192, v192 op_sel_hi:[0,0,0]
	s_nop 1
	v_mfma_scale_f32_16x16x128_f8f6f4 v[146:149], v[26:33], v[194:201], v[146:149], v192, v192 op_sel_hi:[0,0,0]
	s_nop 1
	v_mfma_scale_f32_16x16x128_f8f6f4 v[134:137], v[18:25], v[202:209], v[134:137], v192, v192 op_sel_hi:[0,0,0]
	s_nop 1
	v_mfma_scale_f32_16x16x128_f8f6f4 v[130:133], v[26:33], v[202:209], v[130:133], v192, v192 op_sel_hi:[0,0,0]
	s_nop 1
	v_mfma_scale_f32_16x16x128_f8f6f4 v[118:121], v[18:25], v[210:217], v[118:121], v192, v192 op_sel_hi:[0,0,0]
	s_nop 1
	v_mfma_scale_f32_16x16x128_f8f6f4 v[114:117], v[26:33], v[210:217], v[114:117], v192, v192 op_sel_hi:[0,0,0]
	s_nop 1
	v_mfma_scale_f32_16x16x128_f8f6f4 v[102:105], v[18:25], v[218:225], v[102:105], v192, v192 op_sel_hi:[0,0,0]
	s_nop 1
	v_mfma_scale_f32_16x16x128_f8f6f4 v[98:101], v[26:33], v[218:225], v[98:101], v192, v192 op_sel_hi:[0,0,0]
	s_setprio 0
	s_barrier
	s_add_i32 s44, s44, s49
	v_lshl_add_u64 v[178:179], v[178:179], 0, s[14:15]
	s_mov_b32 m0, s44
	ds_read_b128 v[194:197], v191 offset:49152
	ds_read_b128 v[198:201], v191 offset:50176
	ds_read_b128 v[202:205], v191 offset:51200
	ds_read_b128 v[206:209], v191 offset:52224
	ds_read_b128 v[210:213], v191 offset:53248
	ds_read_b128 v[214:217], v191 offset:54272
	ds_read_b128 v[218:221], v191 offset:55296
	ds_read_b128 v[222:225], v191 offset:56320
	global_load_lds_dwordx4 v[178:179], off
	s_add_i32 m0, s44, 0x2000
	s_add_u32 s42, s42, 0x20080
	v_lshl_add_u64 v[178:179], v[180:181], 0, s[14:15]
	s_addc_u32 s43, s43, 0
	s_add_i32 s44, s45, s49
	global_load_lds_dwordx4 v[178:179], off
	v_lshl_add_u64 v[178:179], s[42:43], 0, v[166:167]
	s_mov_b32 m0, s44
	s_nop 0
	global_load_lds_dwordx4 v[178:179], off
	v_lshl_add_u64 v[178:179], s[42:43], 0, v[162:163]
	s_add_i32 m0, s44, 0x2000
	s_nop 0
	global_load_lds_dwordx4 v[178:179], off
	v_lshl_add_u64 v[178:179], v[182:183], 0, s[14:15]
	s_mov_b32 m0, s57
	s_nop 0
	global_load_lds_dwordx4 v[178:179], off
	v_lshl_add_u64 v[178:179], v[184:185], 0, s[14:15]
	s_mov_b32 m0, s58
	s_nop 0
	global_load_lds_dwordx4 v[178:179], off
	s_waitcnt vmcnt(8)
	s_waitcnt lgkmcnt(0)
	s_barrier
	s_setprio 1
	s_waitcnt lgkmcnt(0)
	s_nop 1
	v_mfma_scale_f32_16x16x128_f8f6f4 v[94:97], v[2:9], v[194:201], v[94:97], v192, v192 op_sel_hi:[0,0,0]
	s_nop 1
	v_mfma_scale_f32_16x16x128_f8f6f4 v[90:93], v[10:17], v[194:201], v[90:93], v192, v192 op_sel_hi:[0,0,0]
	s_nop 1
	v_mfma_scale_f32_16x16x128_f8f6f4 v[78:81], v[2:9], v[202:209], v[78:81], v192, v192 op_sel_hi:[0,0,0]
	s_nop 1
	v_mfma_scale_f32_16x16x128_f8f6f4 v[74:77], v[10:17], v[202:209], v[74:77], v192, v192 op_sel_hi:[0,0,0]
	s_nop 1
	v_mfma_scale_f32_16x16x128_f8f6f4 v[62:65], v[2:9], v[210:217], v[62:65], v192, v192 op_sel_hi:[0,0,0]
	s_nop 1
	v_mfma_scale_f32_16x16x128_f8f6f4 v[58:61], v[10:17], v[210:217], v[58:61], v192, v192 op_sel_hi:[0,0,0]
	s_nop 1
	v_mfma_scale_f32_16x16x128_f8f6f4 v[46:49], v[2:9], v[218:225], v[46:49], v192, v192 op_sel_hi:[0,0,0]
	s_nop 1
	v_mfma_scale_f32_16x16x128_f8f6f4 v[42:45], v[10:17], v[218:225], v[42:45], v192, v192 op_sel_hi:[0,0,0]
	s_nop 1
	v_mfma_scale_f32_16x16x128_f8f6f4 v[86:89], v[18:25], v[194:201], v[86:89], v192, v192 op_sel_hi:[0,0,0]
	s_nop 1
	v_mfma_scale_f32_16x16x128_f8f6f4 v[82:85], v[26:33], v[194:201], v[82:85], v192, v192 op_sel_hi:[0,0,0]
	s_nop 1
	v_mfma_scale_f32_16x16x128_f8f6f4 v[70:73], v[18:25], v[202:209], v[70:73], v192, v192 op_sel_hi:[0,0,0]
	s_nop 1
	v_mfma_scale_f32_16x16x128_f8f6f4 v[66:69], v[26:33], v[202:209], v[66:69], v192, v192 op_sel_hi:[0,0,0]
	s_nop 1
	v_mfma_scale_f32_16x16x128_f8f6f4 v[54:57], v[18:25], v[210:217], v[54:57], v192, v192 op_sel_hi:[0,0,0]
	s_nop 1
	v_mfma_scale_f32_16x16x128_f8f6f4 v[50:53], v[26:33], v[210:217], v[50:53], v192, v192 op_sel_hi:[0,0,0]
	s_nop 1
	v_mfma_scale_f32_16x16x128_f8f6f4 v[38:41], v[18:25], v[218:225], v[38:41], v192, v192 op_sel_hi:[0,0,0]
	s_nop 1
	v_mfma_scale_f32_16x16x128_f8f6f4 v[34:37], v[26:33], v[218:225], v[34:37], v192, v192 op_sel_hi:[0,0,0]
	s_setprio 0
	s_barrier
	s_add_i32 s68, s68, 2
	s_add_u32 s40, s40, 0x100
	s_addc_u32 s41, s41, 0
	s_add_u32 s66, s66, 0x100
	s_addc_u32 s67, s67, 0
	s_cmp_lt_u32 s68, 6
	s_cbranch_scc1 .LBB0_394
	s_nop 15
	s_nop 15
	s_andn2_b64 vcc, exec, s[16:17]
	s_cbranch_vccnz .LBB0_397
	s_barrier

.LBB0_410:
	s_add_u32 s44, s56, s81
	ds_read_b128 v[18:21], v185
	ds_read_b128 v[22:25], v185 offset:1024
	ds_read_b128 v[26:29], v185 offset:2048
	ds_read_b128 v[30:33], v185 offset:3072
	ds_read_b128 v[2:5], v186
	ds_read_b128 v[6:9], v186 offset:1024
	ds_read_b128 v[10:13], v186 offset:2048
	ds_read_b128 v[14:17], v186 offset:3072
	s_addc_u32 s45, s57, 0
	s_add_u32 s82, s44, 0x100
	s_addc_u32 s83, s45, 0
	s_and_b64 s[62:63], s[60:61], exec
	s_cselect_b32 s63, s41, s83
	s_cselect_b32 s62, s79, s82
	s_add_u32 s81, s54, s81
	s_addc_u32 s82, s55, 0
	s_add_u32 s81, s81, 0x100
	s_addc_u32 s82, s82, 0
	s_and_b64 s[60:61], s[60:61], exec
	s_cselect_b32 s61, s39, s82
	s_cselect_b32 s60, s80, s81
	s_add_u32 s82, s44, 0x10080
	s_addc_u32 s83, s45, 0
	v_lshl_add_u64 v[214:215], s[82:83], 0, v[168:169]
	s_add_i32 m0, s53, 0xc000
	ds_read_b128 v[174:177], v187
	ds_read_b128 v[178:181], v187 offset:1024
	ds_read_b128 v[190:193], v187 offset:2048
	ds_read_b128 v[194:197], v187 offset:3072
	ds_read_b128 v[198:201], v187 offset:4096
	ds_read_b128 v[202:205], v187 offset:5120
	ds_read_b128 v[206:209], v187 offset:6144
	ds_read_b128 v[210:213], v187 offset:7168
	global_load_lds_dwordx4 v[214:215], off
	v_lshl_add_u64 v[214:215], s[82:83], 0, v[164:165]
	s_add_i32 m0, s53, 0xe000
	s_nop 0
	global_load_lds_dwordx4 v[214:215], off
	s_waitcnt vmcnt(8)
	s_waitcnt lgkmcnt(0)
	s_barrier
	s_setprio 1
	s_waitcnt lgkmcnt(0)
	s_nop 1
	v_mfma_scale_f32_16x16x128_f8f6f4 v[158:161], v[18:25], v[174:181], v[158:161], v188, v188 op_sel_hi:[0,0,0]
	s_nop 1
	v_mfma_scale_f32_16x16x128_f8f6f4 v[154:157], v[26:33], v[174:181], v[154:157], v188, v188 op_sel_hi:[0,0,0]
	s_nop 1
	v_mfma_scale_f32_16x16x128_f8f6f4 v[142:145], v[18:25], v[190:197], v[142:145], v188, v188 op_sel_hi:[0,0,0]
	s_nop 1
	v_mfma_scale_f32_16x16x128_f8f6f4 v[138:141], v[26:33], v[190:197], v[138:141], v188, v188 op_sel_hi:[0,0,0]
	s_nop 1
	v_mfma_scale_f32_16x16x128_f8f6f4 v[126:129], v[18:25], v[198:205], v[126:129], v188, v188 op_sel_hi:[0,0,0]
	s_nop 1
	v_mfma_scale_f32_16x16x128_f8f6f4 v[122:125], v[26:33], v[198:205], v[122:125], v188, v188 op_sel_hi:[0,0,0]
	s_nop 1
	v_mfma_scale_f32_16x16x128_f8f6f4 v[110:113], v[18:25], v[206:213], v[110:113], v188, v188 op_sel_hi:[0,0,0]
	s_nop 1
	v_mfma_scale_f32_16x16x128_f8f6f4 v[106:109], v[26:33], v[206:213], v[106:109], v188, v188 op_sel_hi:[0,0,0]
	s_nop 1
	v_mfma_scale_f32_16x16x128_f8f6f4 v[150:153], v[2:9], v[174:181], v[150:153], v188, v188 op_sel_hi:[0,0,0]
	s_nop 1
	v_mfma_scale_f32_16x16x128_f8f6f4 v[146:149], v[10:17], v[174:181], v[146:149], v188, v188 op_sel_hi:[0,0,0]
	s_nop 1
	v_mfma_scale_f32_16x16x128_f8f6f4 v[134:137], v[2:9], v[190:197], v[134:137], v188, v188 op_sel_hi:[0,0,0]
	s_nop 1
	v_mfma_scale_f32_16x16x128_f8f6f4 v[130:133], v[10:17], v[190:197], v[130:133], v188, v188 op_sel_hi:[0,0,0]
	s_nop 1
	v_mfma_scale_f32_16x16x128_f8f6f4 v[118:121], v[2:9], v[198:205], v[118:121], v188, v188 op_sel_hi:[0,0,0]
	s_nop 1
	v_mfma_scale_f32_16x16x128_f8f6f4 v[114:117], v[10:17], v[198:205], v[114:117], v188, v188 op_sel_hi:[0,0,0]
	s_nop 1
	v_mfma_scale_f32_16x16x128_f8f6f4 v[102:105], v[2:9], v[206:213], v[102:105], v188, v188 op_sel_hi:[0,0,0]
	s_nop 1
	v_mfma_scale_f32_16x16x128_f8f6f4 v[98:101], v[10:17], v[206:213], v[98:101], v188, v188 op_sel_hi:[0,0,0]
	s_setprio 0
	s_barrier
	s_add_i32 s44, s71, s49
	v_lshl_add_u64 v[174:175], s[60:61], 0, v[166:167]
	s_mov_b32 m0, s44
	ds_read_b128 v[190:193], v187 offset:16384
	ds_read_b128 v[194:197], v187 offset:17408
	ds_read_b128 v[198:201], v187 offset:18432
	ds_read_b128 v[202:205], v187 offset:19456
	ds_read_b128 v[206:209], v187 offset:20480
	ds_read_b128 v[210:213], v187 offset:21504
	ds_read_b128 v[214:217], v187 offset:22528
	ds_read_b128 v[218:221], v187 offset:23552
	global_load_lds_dwordx4 v[174:175], off
	s_add_i32 m0, s44, 0x2000
	s_add_u32 s82, s60, 0x10000
	v_lshl_add_u64 v[176:177], s[60:61], 0, v[162:163]
	s_addc_u32 s83, s61, 0
	s_add_i32 s44, s72, s49
	global_load_lds_dwordx4 v[176:177], off
	v_lshl_add_u64 v[178:179], s[82:83], 0, v[166:167]
	s_mov_b32 m0, s44
	v_lshl_add_u64 v[180:181], s[62:63], 0, v[164:165]
	global_load_lds_dwordx4 v[178:179], off
	v_lshl_add_u64 v[178:179], s[82:83], 0, v[162:163]
	s_add_i32 m0, s44, 0x2000
	s_nop 0
	global_load_lds_dwordx4 v[178:179], off
	v_lshl_add_u64 v[178:179], s[62:63], 0, v[168:169]
	s_mov_b32 m0, s53
	s_nop 0
	global_load_lds_dwordx4 v[178:179], off
	s_mov_b32 m0, s65
	s_nop 0
	global_load_lds_dwordx4 v[180:181], off
	s_waitcnt vmcnt(8)
	s_waitcnt lgkmcnt(0)
	s_barrier
	s_setprio 1
	s_waitcnt lgkmcnt(0)
	s_nop 1
	v_mfma_scale_f32_16x16x128_f8f6f4 v[94:97], v[18:25], v[190:197], v[94:97], v188, v188 op_sel_hi:[0,0,0]
	s_nop 1
	v_mfma_scale_f32_16x16x128_f8f6f4 v[90:93], v[26:33], v[190:197], v[90:93], v188, v188 op_sel_hi:[0,0,0]
	s_nop 1
	v_mfma_scale_f32_16x16x128_f8f6f4 v[78:81], v[18:25], v[198:205], v[78:81], v188, v188 op_sel_hi:[0,0,0]
	s_nop 1
	v_mfma_scale_f32_16x16x128_f8f6f4 v[74:77], v[26:33], v[198:205], v[74:77], v188, v188 op_sel_hi:[0,0,0]
	s_nop 1
	v_mfma_scale_f32_16x16x128_f8f6f4 v[62:65], v[18:25], v[206:213], v[62:65], v188, v188 op_sel_hi:[0,0,0]
	s_nop 1
	v_mfma_scale_f32_16x16x128_f8f6f4 v[58:61], v[26:33], v[206:213], v[58:61], v188, v188 op_sel_hi:[0,0,0]
	s_nop 1
	v_mfma_scale_f32_16x16x128_f8f6f4 v[46:49], v[18:25], v[214:221], v[46:49], v188, v188 op_sel_hi:[0,0,0]
	s_nop 1
	v_mfma_scale_f32_16x16x128_f8f6f4 v[42:45], v[26:33], v[214:221], v[42:45], v188, v188 op_sel_hi:[0,0,0]
	s_nop 1
	v_mfma_scale_f32_16x16x128_f8f6f4 v[86:89], v[2:9], v[190:197], v[86:89], v188, v188 op_sel_hi:[0,0,0]
	s_nop 1
	v_mfma_scale_f32_16x16x128_f8f6f4 v[82:85], v[10:17], v[190:197], v[82:85], v188, v188 op_sel_hi:[0,0,0]
	s_nop 1
	v_mfma_scale_f32_16x16x128_f8f6f4 v[70:73], v[2:9], v[198:205], v[70:73], v188, v188 op_sel_hi:[0,0,0]
	s_nop 1
	v_mfma_scale_f32_16x16x128_f8f6f4 v[66:69], v[10:17], v[198:205], v[66:69], v188, v188 op_sel_hi:[0,0,0]
	s_nop 1
	v_mfma_scale_f32_16x16x128_f8f6f4 v[54:57], v[2:9], v[206:213], v[54:57], v188, v188 op_sel_hi:[0,0,0]
	s_nop 1
	v_mfma_scale_f32_16x16x128_f8f6f4 v[50:53], v[10:17], v[206:213], v[50:53], v188, v188 op_sel_hi:[0,0,0]
	s_nop 1
	v_mfma_scale_f32_16x16x128_f8f6f4 v[38:41], v[2:9], v[214:221], v[38:41], v188, v188 op_sel_hi:[0,0,0]
	s_nop 1
	v_mfma_scale_f32_16x16x128_f8f6f4 v[34:37], v[10:17], v[214:221], v[34:37], v188, v188 op_sel_hi:[0,0,0]
	s_setprio 0
	s_barrier
	s_add_i32 s44, 0, 0x18000
	s_add_i32 s45, 0, 0x1c000
	v_add_u32_e32 v14, s44, v183
	v_add_u32_e32 v30, s45, v183
	ds_read_b128 v[2:5], v14
	ds_read_b128 v[6:9], v14 offset:1024
	ds_read_b128 v[10:13], v14 offset:2048
	ds_read_b128 v[14:17], v14 offset:3072
	ds_read_b128 v[18:21], v30
	ds_read_b128 v[22:25], v30 offset:1024
	ds_read_b128 v[26:29], v30 offset:2048
	ds_read_b128 v[30:33], v30 offset:3072
	s_add_u32 s62, s62, 0x10000
	s_addc_u32 s63, s63, 0
	s_mov_b32 m0, s66
	v_lshl_add_u64 v[222:223], s[62:63], 0, v[168:169]
	ds_read_b128 v[190:193], v187 offset:32768
	ds_read_b128 v[194:197], v187 offset:33792
	ds_read_b128 v[198:201], v187 offset:34816
	ds_read_b128 v[202:205], v187 offset:35840
	ds_read_b128 v[206:209], v187 offset:36864
	ds_read_b128 v[210:213], v187 offset:37888
	ds_read_b128 v[214:217], v187 offset:38912
	ds_read_b128 v[218:221], v187 offset:39936
	global_load_lds_dwordx4 v[222:223], off
	v_lshl_add_u64 v[222:223], s[62:63], 0, v[164:165]
	s_mov_b32 m0, s67
	s_nop 0
	global_load_lds_dwordx4 v[222:223], off
	s_waitcnt vmcnt(8)
	s_waitcnt lgkmcnt(0)
	s_barrier
	s_setprio 1
	s_waitcnt lgkmcnt(0)
	s_nop 1
	v_mfma_scale_f32_16x16x128_f8f6f4 v[158:161], v[2:9], v[190:197], v[158:161], v188, v188 op_sel_hi:[0,0,0]
	s_nop 1
	v_mfma_scale_f32_16x16x128_f8f6f4 v[154:157], v[10:17], v[190:197], v[154:157], v188, v188 op_sel_hi:[0,0,0]
	s_nop 1
	v_mfma_scale_f32_16x16x128_f8f6f4 v[142:145], v[2:9], v[198:205], v[142:145], v188, v188 op_sel_hi:[0,0,0]
	s_nop 1
	v_mfma_scale_f32_16x16x128_f8f6f4 v[138:141], v[10:17], v[198:205], v[138:141], v188, v188 op_sel_hi:[0,0,0]
	s_nop 1
	v_mfma_scale_f32_16x16x128_f8f6f4 v[126:129], v[2:9], v[206:213], v[126:129], v188, v188 op_sel_hi:[0,0,0]
	s_nop 1
	v_mfma_scale_f32_16x16x128_f8f6f4 v[122:125], v[10:17], v[206:213], v[122:125], v188, v188 op_sel_hi:[0,0,0]
	s_nop 1
	v_mfma_scale_f32_16x16x128_f8f6f4 v[110:113], v[2:9], v[214:221], v[110:113], v188, v188 op_sel_hi:[0,0,0]
	s_nop 1
	v_mfma_scale_f32_16x16x128_f8f6f4 v[106:109], v[10:17], v[214:221], v[106:109], v188, v188 op_sel_hi:[0,0,0]
	s_nop 1
	v_mfma_scale_f32_16x16x128_f8f6f4 v[150:153], v[18:25], v[190:197], v[150:153], v188, v188 op_sel_hi:[0,0,0]
	s_nop 1
	v_mfma_scale_f32_16x16x128_f8f6f4 v[146:149], v[26:33], v[190:197], v[146:149], v188, v188 op_sel_hi:[0,0,0]
	s_nop 1
	v_mfma_scale_f32_16x16x128_f8f6f4 v[134:137], v[18:25], v[198:205], v[134:137], v188, v188 op_sel_hi:[0,0,0]
	s_nop 1
	v_mfma_scale_f32_16x16x128_f8f6f4 v[130:133], v[26:33], v[198:205], v[130:133], v188, v188 op_sel_hi:[0,0,0]
	s_nop 1
	v_mfma_scale_f32_16x16x128_f8f6f4 v[118:121], v[18:25], v[206:213], v[118:121], v188, v188 op_sel_hi:[0,0,0]
	s_nop 1
	v_mfma_scale_f32_16x16x128_f8f6f4 v[114:117], v[26:33], v[206:213], v[114:117], v188, v188 op_sel_hi:[0,0,0]
	s_nop 1
	v_mfma_scale_f32_16x16x128_f8f6f4 v[102:105], v[18:25], v[214:221], v[102:105], v188, v188 op_sel_hi:[0,0,0]
	s_nop 1
	v_mfma_scale_f32_16x16x128_f8f6f4 v[98:101], v[26:33], v[214:221], v[98:101], v188, v188 op_sel_hi:[0,0,0]
	s_setprio 0
	s_barrier
	s_add_i32 s44, s44, s49
	v_lshl_add_u64 v[174:175], v[174:175], 0, s[14:15]
	s_mov_b32 m0, s44
	ds_read_b128 v[190:193], v187 offset:49152
	ds_read_b128 v[194:197], v187 offset:50176
	ds_read_b128 v[198:201], v187 offset:51200
	ds_read_b128 v[202:205], v187 offset:52224
	ds_read_b128 v[206:209], v187 offset:53248
	ds_read_b128 v[210:213], v187 offset:54272
	ds_read_b128 v[214:217], v187 offset:55296
	ds_read_b128 v[218:221], v187 offset:56320
	global_load_lds_dwordx4 v[174:175], off
	s_add_i32 m0, s44, 0x2000
	s_add_u32 s60, s60, 0x10080
	v_lshl_add_u64 v[174:175], v[176:177], 0, s[14:15]
	s_addc_u32 s61, s61, 0
	s_add_i32 s44, s45, s49
	global_load_lds_dwordx4 v[174:175], off
	v_lshl_add_u64 v[174:175], s[60:61], 0, v[166:167]
	s_mov_b32 m0, s44
	s_nop 0
	global_load_lds_dwordx4 v[174:175], off
	v_lshl_add_u64 v[174:175], s[60:61], 0, v[162:163]
	s_add_i32 m0, s44, 0x2000
	s_nop 0
	global_load_lds_dwordx4 v[174:175], off
	v_lshl_add_u64 v[174:175], v[178:179], 0, s[14:15]
	s_mov_b32 m0, s69
	s_nop 0
	global_load_lds_dwordx4 v[174:175], off
	v_lshl_add_u64 v[174:175], v[180:181], 0, s[14:15]
	s_mov_b32 m0, s70
	s_nop 0
	global_load_lds_dwordx4 v[174:175], off
	s_waitcnt vmcnt(8)
	s_waitcnt lgkmcnt(0)
	s_barrier
	s_setprio 1
	s_waitcnt lgkmcnt(0)
	s_nop 1
	v_mfma_scale_f32_16x16x128_f8f6f4 v[94:97], v[2:9], v[190:197], v[94:97], v188, v188 op_sel_hi:[0,0,0]
	s_nop 1
	v_mfma_scale_f32_16x16x128_f8f6f4 v[90:93], v[10:17], v[190:197], v[90:93], v188, v188 op_sel_hi:[0,0,0]
	s_nop 1
	v_mfma_scale_f32_16x16x128_f8f6f4 v[78:81], v[2:9], v[198:205], v[78:81], v188, v188 op_sel_hi:[0,0,0]
	s_nop 1
	v_mfma_scale_f32_16x16x128_f8f6f4 v[74:77], v[10:17], v[198:205], v[74:77], v188, v188 op_sel_hi:[0,0,0]
	s_nop 1
	v_mfma_scale_f32_16x16x128_f8f6f4 v[62:65], v[2:9], v[206:213], v[62:65], v188, v188 op_sel_hi:[0,0,0]
	s_nop 1
	v_mfma_scale_f32_16x16x128_f8f6f4 v[58:61], v[10:17], v[206:213], v[58:61], v188, v188 op_sel_hi:[0,0,0]
	s_nop 1
	v_mfma_scale_f32_16x16x128_f8f6f4 v[46:49], v[2:9], v[214:221], v[46:49], v188, v188 op_sel_hi:[0,0,0]
	s_nop 1
	v_mfma_scale_f32_16x16x128_f8f6f4 v[42:45], v[10:17], v[214:221], v[42:45], v188, v188 op_sel_hi:[0,0,0]
	s_nop 1
	v_mfma_scale_f32_16x16x128_f8f6f4 v[86:89], v[18:25], v[190:197], v[86:89], v188, v188 op_sel_hi:[0,0,0]
	s_nop 1
	v_mfma_scale_f32_16x16x128_f8f6f4 v[82:85], v[26:33], v[190:197], v[82:85], v188, v188 op_sel_hi:[0,0,0]
	s_nop 1
	v_mfma_scale_f32_16x16x128_f8f6f4 v[70:73], v[18:25], v[198:205], v[70:73], v188, v188 op_sel_hi:[0,0,0]
	s_nop 1
	v_mfma_scale_f32_16x16x128_f8f6f4 v[66:69], v[26:33], v[198:205], v[66:69], v188, v188 op_sel_hi:[0,0,0]
	s_nop 1
	v_mfma_scale_f32_16x16x128_f8f6f4 v[54:57], v[18:25], v[206:213], v[54:57], v188, v188 op_sel_hi:[0,0,0]
	s_nop 1
	v_mfma_scale_f32_16x16x128_f8f6f4 v[50:53], v[26:33], v[206:213], v[50:53], v188, v188 op_sel_hi:[0,0,0]
	s_nop 1
	v_mfma_scale_f32_16x16x128_f8f6f4 v[38:41], v[18:25], v[214:221], v[38:41], v188, v188 op_sel_hi:[0,0,0]
	s_nop 1
	v_mfma_scale_f32_16x16x128_f8f6f4 v[34:37], v[26:33], v[214:221], v[34:37], v188, v188 op_sel_hi:[0,0,0]
	s_setprio 0
	s_barrier
	s_movk_i32 s81, 0x100
	s_and_b64 vcc, exec, s[58:59]
	s_mov_b64 s[60:61], -1
	s_mov_b64 s[58:59], 0
	s_cbranch_vccnz .LBB0_410
	s_nop 15
	s_nop 15
	s_andn2_b64 vcc, exec, s[16:17]
	s_cbranch_vccnz .LBB0_413
	s_barrier

.LBB0_784:
	ds_read_b128 v[158:161], v196
	ds_read_b128 v[154:157], v196 offset:1024
	ds_read_b128 v[22:25], v196 offset:2048
	ds_read_b128 v[18:21], v196 offset:3072
	ds_read_b128 v[14:17], v197
	ds_read_b128 v[10:13], v197 offset:1024
	ds_read_b128 v[6:9], v197 offset:2048
	ds_read_b128 v[2:5], v197 offset:3072
	v_lshl_add_u64 v[186:187], v[162:163], 0, s[58:59]
	s_add_i32 s75, s49, 0xc000
	v_lshl_add_u64 v[188:189], v[186:187], 0, s[18:19]
	s_mov_b32 m0, s75
	ds_read_b128 v[190:193], v198
	ds_read_b128 v[200:203], v198 offset:1024
	ds_read_b128 v[204:207], v198 offset:2048
	ds_read_b128 v[208:211], v198 offset:3072
	ds_read_b128 v[212:215], v198 offset:4096
	ds_read_b128 v[216:219], v198 offset:5120
	ds_read_b128 v[220:223], v198 offset:6144
	ds_read_b128 v[224:227], v198 offset:7168
	global_load_lds_dwordx4 v[188:189], off
	v_lshl_add_u64 v[188:189], v[164:165], 0, s[58:59]
	s_add_i32 s76, s49, 0xe000
	v_lshl_add_u64 v[228:229], v[188:189], 0, s[18:19]
	s_mov_b32 m0, s76
	s_nop 0
	global_load_lds_dwordx4 v[228:229], off
	s_waitcnt vmcnt(8)
	s_waitcnt lgkmcnt(0)
	s_barrier
	s_setprio 1
	s_waitcnt lgkmcnt(0)
	s_nop 1
	v_mfma_f32_16x16x32_bf16 v[150:153], v[158:161], v[190:193], v[150:153]
	s_nop 0
	s_nop 1
	v_mfma_f32_16x16x32_bf16 v[150:153], v[154:157], v[200:203], v[150:153]
	s_nop 1
	v_mfma_f32_16x16x32_bf16 v[146:149], v[22:25], v[190:193], v[146:149]
	s_nop 0
	s_nop 1
	v_mfma_f32_16x16x32_bf16 v[146:149], v[18:21], v[200:203], v[146:149]
	s_nop 1
	v_mfma_f32_16x16x32_bf16 v[142:145], v[158:161], v[204:207], v[142:145]
	s_nop 0
	s_nop 1
	v_mfma_f32_16x16x32_bf16 v[142:145], v[154:157], v[208:211], v[142:145]
	s_nop 1
	v_mfma_f32_16x16x32_bf16 v[138:141], v[22:25], v[204:207], v[138:141]
	s_nop 0
	s_nop 1
	v_mfma_f32_16x16x32_bf16 v[138:141], v[18:21], v[208:211], v[138:141]
	s_nop 1
	v_mfma_f32_16x16x32_bf16 v[134:137], v[158:161], v[212:215], v[134:137]
	s_nop 0
	s_nop 1
	v_mfma_f32_16x16x32_bf16 v[134:137], v[154:157], v[216:219], v[134:137]
	s_nop 1
	v_mfma_f32_16x16x32_bf16 v[122:125], v[22:25], v[212:215], v[122:125]
	s_nop 0
	s_nop 1
	v_mfma_f32_16x16x32_bf16 v[122:125], v[18:21], v[216:219], v[122:125]
	s_nop 1
	v_mfma_f32_16x16x32_bf16 v[106:109], v[158:161], v[220:223], v[106:109]
	s_nop 0
	s_nop 1
	v_mfma_f32_16x16x32_bf16 v[106:109], v[154:157], v[224:227], v[106:109]
	s_nop 1
	v_mfma_f32_16x16x32_bf16 v[98:101], v[22:25], v[220:223], v[98:101]
	s_nop 0
	s_nop 1
	v_mfma_f32_16x16x32_bf16 v[98:101], v[18:21], v[224:227], v[98:101]
	s_nop 1
	v_mfma_f32_16x16x32_bf16 v[130:133], v[14:17], v[190:193], v[130:133]
	s_nop 0
	s_nop 1
	v_mfma_f32_16x16x32_bf16 v[130:133], v[10:13], v[200:203], v[130:133]
	s_nop 1
	v_mfma_f32_16x16x32_bf16 v[126:129], v[6:9], v[190:193], v[126:129]
	s_nop 0
	s_nop 1
	v_mfma_f32_16x16x32_bf16 v[126:129], v[2:5], v[200:203], v[126:129]
	s_nop 1
	v_mfma_f32_16x16x32_bf16 v[118:121], v[14:17], v[204:207], v[118:121]
	s_nop 0
	s_nop 1
	v_mfma_f32_16x16x32_bf16 v[118:121], v[10:13], v[208:211], v[118:121]
	s_nop 1
	v_mfma_f32_16x16x32_bf16 v[114:117], v[6:9], v[204:207], v[114:117]
	s_nop 0
	s_nop 1
	v_mfma_f32_16x16x32_bf16 v[114:117], v[2:5], v[208:211], v[114:117]
	s_nop 1
	v_mfma_f32_16x16x32_bf16 v[110:113], v[14:17], v[212:215], v[110:113]
	s_nop 0
	s_nop 1
	v_mfma_f32_16x16x32_bf16 v[110:113], v[10:13], v[216:219], v[110:113]
	s_nop 1
	v_mfma_f32_16x16x32_bf16 v[102:105], v[6:9], v[212:215], v[102:105]
	s_nop 0
	s_nop 1
	v_mfma_f32_16x16x32_bf16 v[102:105], v[2:5], v[216:219], v[102:105]
	s_nop 1
	v_mfma_f32_16x16x32_bf16 v[94:97], v[14:17], v[220:223], v[94:97]
	s_nop 0
	s_nop 1
	v_mfma_f32_16x16x32_bf16 v[94:97], v[10:13], v[224:227], v[94:97]
	s_nop 1
	v_mfma_f32_16x16x32_bf16 v[90:93], v[6:9], v[220:223], v[90:93]
	s_nop 0
	s_nop 1
	v_mfma_f32_16x16x32_bf16 v[90:93], v[2:5], v[224:227], v[90:93]
	s_setprio 0
	s_barrier
	v_lshl_add_u64 v[190:191], v[166:167], 0, s[58:59]
	s_add_i32 s77, s69, s46
	v_lshl_add_u64 v[192:193], v[190:191], 0, s[22:23]
	s_mov_b32 m0, s77
	ds_read_b128 v[200:203], v198 offset:16384
	ds_read_b128 v[204:207], v198 offset:17408
	ds_read_b128 v[208:211], v198 offset:18432
	ds_read_b128 v[212:215], v198 offset:19456
	ds_read_b128 v[216:219], v198 offset:20480
	ds_read_b128 v[220:223], v198 offset:21504
	ds_read_b128 v[224:227], v198 offset:22528
	ds_read_b128 v[228:231], v198 offset:23552
	global_load_lds_dwordx4 v[192:193], off
	v_lshl_add_u64 v[192:193], v[168:169], 0, s[58:59]
	s_add_i32 s78, s77, 0x2000
	v_lshl_add_u64 v[232:233], v[192:193], 0, s[22:23]
	s_mov_b32 m0, s78
	s_add_i32 s79, s70, s46
	global_load_lds_dwordx4 v[232:233], off
	v_lshl_add_u64 v[232:233], v[190:191], 0, s[24:25]
	s_mov_b32 m0, s79
	s_add_i32 s80, s79, 0x2000
	global_load_lds_dwordx4 v[232:233], off
	v_lshl_add_u64 v[232:233], v[192:193], 0, s[24:25]
	s_mov_b32 m0, s80
	s_nop 0
	global_load_lds_dwordx4 v[232:233], off
	v_lshl_add_u64 v[232:233], v[186:187], 0, s[22:23]
	s_mov_b32 m0, s49
	s_nop 0
	global_load_lds_dwordx4 v[232:233], off
	v_lshl_add_u64 v[232:233], v[188:189], 0, s[22:23]
	s_mov_b32 m0, s60
	s_nop 0
	global_load_lds_dwordx4 v[232:233], off
	s_waitcnt vmcnt(8)
	s_waitcnt lgkmcnt(0)
	s_barrier
	s_setprio 1
	s_waitcnt lgkmcnt(0)
	s_nop 1
	v_mfma_f32_16x16x32_bf16 v[86:89], v[158:161], v[200:203], v[86:89]
	s_nop 0
	s_nop 1
	v_mfma_f32_16x16x32_bf16 v[86:89], v[154:157], v[204:207], v[86:89]
	s_nop 1
	v_mfma_f32_16x16x32_bf16 v[82:85], v[22:25], v[200:203], v[82:85]
	s_nop 0
	s_nop 1
	v_mfma_f32_16x16x32_bf16 v[82:85], v[18:21], v[204:207], v[82:85]
	s_nop 1
	v_mfma_f32_16x16x32_bf16 v[78:81], v[158:161], v[208:211], v[78:81]
	s_nop 0
	s_nop 1
	v_mfma_f32_16x16x32_bf16 v[78:81], v[154:157], v[212:215], v[78:81]
	s_nop 1
	v_mfma_f32_16x16x32_bf16 v[74:77], v[22:25], v[208:211], v[74:77]
	s_nop 0
	s_nop 1
	v_mfma_f32_16x16x32_bf16 v[74:77], v[18:21], v[212:215], v[74:77]
	s_nop 1
	v_mfma_f32_16x16x32_bf16 v[70:73], v[158:161], v[216:219], v[70:73]
	s_nop 0
	s_nop 1
	v_mfma_f32_16x16x32_bf16 v[70:73], v[154:157], v[220:223], v[70:73]
	s_nop 1
	v_mfma_f32_16x16x32_bf16 v[58:61], v[22:25], v[216:219], v[58:61]
	s_nop 0
	s_nop 1
	v_mfma_f32_16x16x32_bf16 v[58:61], v[18:21], v[220:223], v[58:61]
	s_nop 1
	v_mfma_f32_16x16x32_bf16 v[42:45], v[158:161], v[224:227], v[42:45]
	s_nop 0
	s_nop 1
	v_mfma_f32_16x16x32_bf16 v[42:45], v[154:157], v[228:231], v[42:45]
	s_nop 1
	v_mfma_f32_16x16x32_bf16 v[34:37], v[22:25], v[224:227], v[34:37]
	s_nop 0
	s_nop 1
	v_mfma_f32_16x16x32_bf16 v[34:37], v[18:21], v[228:231], v[34:37]
	s_nop 1
	v_mfma_f32_16x16x32_bf16 v[66:69], v[14:17], v[200:203], v[66:69]
	s_nop 0
	s_nop 1
	v_mfma_f32_16x16x32_bf16 v[66:69], v[10:13], v[204:207], v[66:69]
	s_nop 1
	v_mfma_f32_16x16x32_bf16 v[62:65], v[6:9], v[200:203], v[62:65]
	s_nop 0
	s_nop 1
	v_mfma_f32_16x16x32_bf16 v[62:65], v[2:5], v[204:207], v[62:65]
	s_nop 1
	v_mfma_f32_16x16x32_bf16 v[54:57], v[14:17], v[208:211], v[54:57]
	s_nop 0
	s_nop 1
	v_mfma_f32_16x16x32_bf16 v[54:57], v[10:13], v[212:215], v[54:57]
	s_nop 1
	v_mfma_f32_16x16x32_bf16 v[50:53], v[6:9], v[208:211], v[50:53]
	s_nop 0
	s_nop 1
	v_mfma_f32_16x16x32_bf16 v[50:53], v[2:5], v[212:215], v[50:53]
	s_nop 1
	v_mfma_f32_16x16x32_bf16 v[46:49], v[14:17], v[216:219], v[46:49]
	s_nop 0
	s_nop 1
	v_mfma_f32_16x16x32_bf16 v[46:49], v[10:13], v[220:223], v[46:49]
	s_nop 1
	v_mfma_f32_16x16x32_bf16 v[38:41], v[6:9], v[216:219], v[38:41]
	s_nop 0
	s_nop 1
	v_mfma_f32_16x16x32_bf16 v[38:41], v[2:5], v[220:223], v[38:41]
	s_nop 1
	v_mfma_f32_16x16x32_bf16 v[30:33], v[14:17], v[224:227], v[30:33]
	s_nop 0
	s_nop 1
	v_mfma_f32_16x16x32_bf16 v[30:33], v[10:13], v[228:231], v[30:33]
	s_nop 1
	v_mfma_f32_16x16x32_bf16 v[26:29], v[6:9], v[224:227], v[26:29]
	s_nop 0
	s_nop 1
	v_mfma_f32_16x16x32_bf16 v[26:29], v[2:5], v[228:231], v[26:29]
	s_setprio 0
	s_barrier
	s_add_i32 s82, 0, 0x18000
	s_add_i32 s84, 0, 0x1c000
	v_add_u32_e32 v199, s82, v194
	v_add_u32_e32 v200, s84, v194
	ds_read_b128 v[2:5], v199
	ds_read_b128 v[6:9], v199 offset:1024
	ds_read_b128 v[10:13], v199 offset:2048
	ds_read_b128 v[14:17], v199 offset:3072
	ds_read_b128 v[18:21], v200
	ds_read_b128 v[22:25], v200 offset:1024
	ds_read_b128 v[154:157], v200 offset:2048
	ds_read_b128 v[158:161], v200 offset:3072
	s_mov_b32 m0, s61
	v_lshl_add_u64 v[234:235], v[186:187], 0, s[24:25]
	ds_read_b128 v[202:205], v198 offset:32768
	ds_read_b128 v[206:209], v198 offset:33792
	ds_read_b128 v[210:213], v198 offset:34816
	ds_read_b128 v[214:217], v198 offset:35840
	ds_read_b128 v[218:221], v198 offset:36864
	ds_read_b128 v[222:225], v198 offset:37888
	ds_read_b128 v[226:229], v198 offset:38912
	ds_read_b128 v[230:233], v198 offset:39936
	global_load_lds_dwordx4 v[234:235], off
	v_lshl_add_u64 v[234:235], v[188:189], 0, s[24:25]
	s_mov_b32 m0, s62
	s_nop 0
	global_load_lds_dwordx4 v[234:235], off
	s_waitcnt vmcnt(8)
	s_waitcnt lgkmcnt(0)
	s_barrier
	s_setprio 1
	s_waitcnt lgkmcnt(0)
	s_nop 1
	v_mfma_f32_16x16x32_bf16 v[150:153], v[2:5], v[202:205], v[150:153]
	s_nop 0
	s_nop 1
	v_mfma_f32_16x16x32_bf16 v[150:153], v[6:9], v[206:209], v[150:153]
	s_nop 1
	v_mfma_f32_16x16x32_bf16 v[146:149], v[10:13], v[202:205], v[146:149]
	s_nop 0
	s_nop 1
	v_mfma_f32_16x16x32_bf16 v[146:149], v[14:17], v[206:209], v[146:149]
	s_nop 1
	v_mfma_f32_16x16x32_bf16 v[142:145], v[2:5], v[210:213], v[142:145]
	s_nop 0
	s_nop 1
	v_mfma_f32_16x16x32_bf16 v[142:145], v[6:9], v[214:217], v[142:145]
	s_nop 1
	v_mfma_f32_16x16x32_bf16 v[138:141], v[10:13], v[210:213], v[138:141]
	s_nop 0
	s_nop 1
	v_mfma_f32_16x16x32_bf16 v[138:141], v[14:17], v[214:217], v[138:141]
	s_nop 1
	v_mfma_f32_16x16x32_bf16 v[134:137], v[2:5], v[218:221], v[134:137]
	s_nop 0
	s_nop 1
	v_mfma_f32_16x16x32_bf16 v[134:137], v[6:9], v[222:225], v[134:137]
	s_nop 1
	v_mfma_f32_16x16x32_bf16 v[122:125], v[10:13], v[218:221], v[122:125]
	s_nop 0
	s_nop 1
	v_mfma_f32_16x16x32_bf16 v[122:125], v[14:17], v[222:225], v[122:125]
	s_nop 1
	v_mfma_f32_16x16x32_bf16 v[106:109], v[2:5], v[226:229], v[106:109]
	s_nop 0
	s_nop 1
	v_mfma_f32_16x16x32_bf16 v[106:109], v[6:9], v[230:233], v[106:109]
	s_nop 1
	v_mfma_f32_16x16x32_bf16 v[98:101], v[10:13], v[226:229], v[98:101]
	s_nop 0
	s_nop 1
	v_mfma_f32_16x16x32_bf16 v[98:101], v[14:17], v[230:233], v[98:101]
	s_nop 1
	v_mfma_f32_16x16x32_bf16 v[130:133], v[18:21], v[202:205], v[130:133]
	s_nop 0
	s_nop 1
	v_mfma_f32_16x16x32_bf16 v[130:133], v[22:25], v[206:209], v[130:133]
	s_nop 1
	v_mfma_f32_16x16x32_bf16 v[126:129], v[154:157], v[202:205], v[126:129]
	s_nop 0
	s_nop 1
	v_mfma_f32_16x16x32_bf16 v[126:129], v[158:161], v[206:209], v[126:129]
	s_nop 1
	v_mfma_f32_16x16x32_bf16 v[118:121], v[18:21], v[210:213], v[118:121]
	s_nop 0
	s_nop 1
	v_mfma_f32_16x16x32_bf16 v[118:121], v[22:25], v[214:217], v[118:121]
	s_nop 1
	v_mfma_f32_16x16x32_bf16 v[114:117], v[154:157], v[210:213], v[114:117]
	s_nop 0
	s_nop 1
	v_mfma_f32_16x16x32_bf16 v[114:117], v[158:161], v[214:217], v[114:117]
	s_nop 1
	v_mfma_f32_16x16x32_bf16 v[110:113], v[18:21], v[218:221], v[110:113]
	s_nop 0
	s_nop 1
	v_mfma_f32_16x16x32_bf16 v[110:113], v[22:25], v[222:225], v[110:113]
	s_nop 1
	v_mfma_f32_16x16x32_bf16 v[102:105], v[154:157], v[218:221], v[102:105]
	s_nop 0
	s_nop 1
	v_mfma_f32_16x16x32_bf16 v[102:105], v[158:161], v[222:225], v[102:105]
	s_nop 1
	v_mfma_f32_16x16x32_bf16 v[94:97], v[18:21], v[226:229], v[94:97]
	s_nop 0
	s_nop 1
	v_mfma_f32_16x16x32_bf16 v[94:97], v[22:25], v[230:233], v[94:97]
	s_nop 1
	v_mfma_f32_16x16x32_bf16 v[90:93], v[154:157], v[226:229], v[90:93]
	s_nop 0
	s_nop 1
	v_mfma_f32_16x16x32_bf16 v[90:93], v[158:161], v[230:233], v[90:93]
	s_setprio 0
	s_barrier
	s_add_i32 s82, s82, s46
	v_lshl_add_u64 v[234:235], v[190:191], 0, s[26:27]
	s_mov_b32 m0, s82
	s_add_i32 s83, s82, 0x2000
	ds_read_b128 v[202:205], v198 offset:49152
	ds_read_b128 v[206:209], v198 offset:50176
	ds_read_b128 v[210:213], v198 offset:51200
	ds_read_b128 v[214:217], v198 offset:52224
	ds_read_b128 v[218:221], v198 offset:53248
	ds_read_b128 v[222:225], v198 offset:54272
	ds_read_b128 v[226:229], v198 offset:55296
	ds_read_b128 v[230:233], v198 offset:56320
	global_load_lds_dwordx4 v[234:235], off
	v_lshl_add_u64 v[234:235], v[192:193], 0, s[26:27]
	s_mov_b32 m0, s83
	s_add_i32 s84, s84, s46
	global_load_lds_dwordx4 v[234:235], off
	v_lshl_add_u64 v[190:191], v[190:191], 0, s[36:37]
	s_mov_b32 m0, s84
	s_add_i32 s85, s84, 0x2000
	global_load_lds_dwordx4 v[190:191], off
	v_lshl_add_u64 v[190:191], v[192:193], 0, s[36:37]
	s_mov_b32 m0, s85
	v_lshl_add_u64 v[186:187], v[186:187], 0, s[26:27]
	global_load_lds_dwordx4 v[190:191], off
	s_mov_b32 m0, s67
	s_nop 0
	global_load_lds_dwordx4 v[186:187], off
	v_lshl_add_u64 v[186:187], v[188:189], 0, s[26:27]
	s_mov_b32 m0, s68
	s_nop 0
	global_load_lds_dwordx4 v[186:187], off
	s_waitcnt vmcnt(8)
	s_waitcnt lgkmcnt(0)
	s_barrier
	s_setprio 1
	s_waitcnt lgkmcnt(0)
	s_nop 1
	v_mfma_f32_16x16x32_bf16 v[86:89], v[2:5], v[202:205], v[86:89]
	s_nop 0
	s_nop 1
	v_mfma_f32_16x16x32_bf16 v[86:89], v[6:9], v[206:209], v[86:89]
	s_nop 1
	v_mfma_f32_16x16x32_bf16 v[82:85], v[10:13], v[202:205], v[82:85]
	s_nop 0
	s_nop 1
	v_mfma_f32_16x16x32_bf16 v[82:85], v[14:17], v[206:209], v[82:85]
	s_nop 1
	v_mfma_f32_16x16x32_bf16 v[78:81], v[2:5], v[210:213], v[78:81]
	s_nop 0
	s_nop 1
	v_mfma_f32_16x16x32_bf16 v[78:81], v[6:9], v[214:217], v[78:81]
	s_nop 1
	v_mfma_f32_16x16x32_bf16 v[74:77], v[10:13], v[210:213], v[74:77]
	s_nop 0
	s_nop 1
	v_mfma_f32_16x16x32_bf16 v[74:77], v[14:17], v[214:217], v[74:77]
	s_nop 1
	v_mfma_f32_16x16x32_bf16 v[70:73], v[2:5], v[218:221], v[70:73]
	s_nop 0
	s_nop 1
	v_mfma_f32_16x16x32_bf16 v[70:73], v[6:9], v[222:225], v[70:73]
	s_nop 1
	v_mfma_f32_16x16x32_bf16 v[58:61], v[10:13], v[218:221], v[58:61]
	s_nop 0
	s_nop 1
	v_mfma_f32_16x16x32_bf16 v[58:61], v[14:17], v[222:225], v[58:61]
	s_nop 1
	v_mfma_f32_16x16x32_bf16 v[42:45], v[2:5], v[226:229], v[42:45]
	s_nop 0
	s_nop 1
	v_mfma_f32_16x16x32_bf16 v[42:45], v[6:9], v[230:233], v[42:45]
	s_nop 1
	v_mfma_f32_16x16x32_bf16 v[34:37], v[10:13], v[226:229], v[34:37]
	s_nop 0
	s_nop 1
	v_mfma_f32_16x16x32_bf16 v[34:37], v[14:17], v[230:233], v[34:37]
	s_nop 1
	v_mfma_f32_16x16x32_bf16 v[66:69], v[18:21], v[202:205], v[66:69]
	s_nop 0
	s_nop 1
	v_mfma_f32_16x16x32_bf16 v[66:69], v[22:25], v[206:209], v[66:69]
	s_nop 1
	v_mfma_f32_16x16x32_bf16 v[62:65], v[154:157], v[202:205], v[62:65]
	s_nop 0
	s_nop 1
	v_mfma_f32_16x16x32_bf16 v[62:65], v[158:161], v[206:209], v[62:65]
	s_nop 1
	v_mfma_f32_16x16x32_bf16 v[54:57], v[18:21], v[210:213], v[54:57]
	s_nop 0
	s_nop 1
	v_mfma_f32_16x16x32_bf16 v[54:57], v[22:25], v[214:217], v[54:57]
	s_nop 1
	v_mfma_f32_16x16x32_bf16 v[50:53], v[154:157], v[210:213], v[50:53]
	s_nop 0
	s_nop 1
	v_mfma_f32_16x16x32_bf16 v[50:53], v[158:161], v[214:217], v[50:53]
	s_nop 1
	v_mfma_f32_16x16x32_bf16 v[46:49], v[18:21], v[218:221], v[46:49]
	s_nop 0
	s_nop 1
	v_mfma_f32_16x16x32_bf16 v[46:49], v[22:25], v[222:225], v[46:49]
	s_nop 1
	v_mfma_f32_16x16x32_bf16 v[38:41], v[154:157], v[218:221], v[38:41]
	s_nop 0
	s_nop 1
	v_mfma_f32_16x16x32_bf16 v[38:41], v[158:161], v[222:225], v[38:41]
	s_nop 1
	v_mfma_f32_16x16x32_bf16 v[30:33], v[18:21], v[226:229], v[30:33]
	s_nop 0
	s_nop 1
	v_mfma_f32_16x16x32_bf16 v[30:33], v[22:25], v[230:233], v[30:33]
	s_nop 1
	v_mfma_f32_16x16x32_bf16 v[26:29], v[154:157], v[226:229], v[26:29]
	s_nop 0
	s_nop 1
	v_mfma_f32_16x16x32_bf16 v[26:29], v[158:161], v[230:233], v[26:29]
	s_setprio 0
	s_barrier
	s_add_i32 s81, s81, 2
	s_add_u32 s58, s58, 0x100
	s_addc_u32 s59, s59, 0
	s_cmp_lt_u32 s81, 30
	s_cbranch_scc1 .LBB0_784
	s_add_u32 s81, s56, 0x1100
	s_addc_u32 s86, s57, 0
	s_mov_b32 s87, 30
.LBB0_786:
	ds_read_b128 v[20:23], v196
	ds_read_b128 v[166:169], v196 offset:1024
	ds_read_b128 v[14:17], v196 offset:2048
	ds_read_b128 v[162:165], v196 offset:3072
	ds_read_b128 v[8:11], v197
	ds_read_b128 v[154:157], v197 offset:1024
	ds_read_b128 v[2:5], v197 offset:2048
	ds_read_b128 v[158:161], v197 offset:3072
	s_add_u32 s44, s54, 0x1100
	s_addc_u32 s45, s55, 0
	s_cmp_eq_u32 s87, 44
	s_cselect_b32 s59, s9, s45
	s_cselect_b32 s58, s8, s44
	s_cselect_b32 s57, s53, s86
	s_cselect_b32 s56, s52, s81
	s_mov_b32 m0, s75
	v_lshl_add_u64 v[6:7], s[54:55], 0, v[178:179]
	ds_read_b128 v[186:189], v198
	ds_read_b128 v[190:193], v198 offset:1024
	ds_read_b128 v[202:205], v198 offset:2048
	ds_read_b128 v[218:221], v198 offset:3072
	ds_read_b128 v[208:211], v198 offset:4096
	ds_read_b128 v[222:225], v198 offset:5120
	ds_read_b128 v[214:217], v198 offset:6144
	ds_read_b128 v[226:229], v198 offset:7168
	global_load_lds_dwordx4 v[6:7], off
	v_lshl_add_u64 v[6:7], s[54:55], 0, v[180:181]
	s_mov_b32 m0, s76
	s_nop 0
	global_load_lds_dwordx4 v[6:7], off
	s_waitcnt vmcnt(8)
	s_waitcnt lgkmcnt(0)
	s_barrier
	s_setprio 1
	s_waitcnt lgkmcnt(0)
	v_mov_b32_e32 v24, v166
	v_mov_b32_e32 v25, v167
	s_nop 1
	v_mfma_scale_f32_16x16x128_f8f6f4 v[150:153], v[20:25], v[186:191], v[150:153], v168, v192 op_sel_hi:[0,0,0] cbsz:2 blgp:2
	v_mov_b32_e32 v18, v162
	v_mov_b32_e32 v19, v163
	s_nop 1
	v_mfma_scale_f32_16x16x128_f8f6f4 v[146:149], v[14:19], v[186:191], v[146:149], v164, v192 op_sel_hi:[0,0,0] cbsz:2 blgp:2
	v_mov_b32_e32 v206, v218
	v_mov_b32_e32 v207, v219
	s_nop 1
	v_mfma_scale_f32_16x16x128_f8f6f4 v[142:145], v[20:25], v[202:207], v[142:145], v168, v220 op_sel_hi:[0,0,0] cbsz:2 blgp:2
	s_nop 1
	v_mfma_scale_f32_16x16x128_f8f6f4 v[138:141], v[14:19], v[202:207], v[138:141], v164, v220 op_sel_hi:[0,0,0] cbsz:2 blgp:2
	v_mov_b32_e32 v212, v222
	v_mov_b32_e32 v213, v223
	s_nop 1
	v_mfma_scale_f32_16x16x128_f8f6f4 v[134:137], v[20:25], v[208:213], v[134:137], v168, v224 op_sel_hi:[0,0,0] cbsz:2 blgp:2
	s_nop 1
	v_mfma_scale_f32_16x16x128_f8f6f4 v[122:125], v[14:19], v[208:213], v[122:125], v164, v224 op_sel_hi:[0,0,0] cbsz:2 blgp:2
	v_mov_b32_e32 v218, v226
	v_mov_b32_e32 v219, v227
	s_nop 1
	v_mfma_scale_f32_16x16x128_f8f6f4 v[106:109], v[20:25], v[214:219], v[106:109], v168, v228 op_sel_hi:[0,0,0] cbsz:2 blgp:2
	s_nop 1
	v_mfma_scale_f32_16x16x128_f8f6f4 v[98:101], v[14:19], v[214:219], v[98:101], v164, v228 op_sel_hi:[0,0,0] cbsz:2 blgp:2
	v_mov_b32_e32 v12, v154
	v_mov_b32_e32 v13, v155
	s_nop 1
	v_mfma_scale_f32_16x16x128_f8f6f4 v[130:133], v[8:13], v[186:191], v[130:133], v156, v192 op_sel_hi:[0,0,0] cbsz:2 blgp:2
	v_mov_b32_e32 v6, v158
	v_mov_b32_e32 v7, v159
	s_nop 1
	v_mfma_scale_f32_16x16x128_f8f6f4 v[126:129], v[2:7], v[186:191], v[126:129], v160, v192 op_sel_hi:[0,0,0] cbsz:2 blgp:2
	s_nop 1
	v_mfma_scale_f32_16x16x128_f8f6f4 v[118:121], v[8:13], v[202:207], v[118:121], v156, v220 op_sel_hi:[0,0,0] cbsz:2 blgp:2
	s_nop 1
	v_mfma_scale_f32_16x16x128_f8f6f4 v[114:117], v[2:7], v[202:207], v[114:117], v160, v220 op_sel_hi:[0,0,0] cbsz:2 blgp:2
	s_nop 1
	v_mfma_scale_f32_16x16x128_f8f6f4 v[110:113], v[8:13], v[208:213], v[110:113], v156, v224 op_sel_hi:[0,0,0] cbsz:2 blgp:2
	s_nop 1
	v_mfma_scale_f32_16x16x128_f8f6f4 v[102:105], v[2:7], v[208:213], v[102:105], v160, v224 op_sel_hi:[0,0,0] cbsz:2 blgp:2
	s_nop 1
	v_mfma_scale_f32_16x16x128_f8f6f4 v[94:97], v[8:13], v[214:219], v[94:97], v156, v228 op_sel_hi:[0,0,0] cbsz:2 blgp:2
	s_nop 1
	v_mfma_scale_f32_16x16x128_f8f6f4 v[90:93], v[2:7], v[214:219], v[90:93], v160, v228 op_sel_hi:[0,0,0] cbsz:2 blgp:2
	s_setprio 0
	s_barrier
	s_mov_b32 m0, s77
	v_lshl_add_u64 v[186:187], s[56:57], 0, v[172:173]
	s_add_u32 s44, s56, 0xc0000
	ds_read_b128 v[202:205], v198 offset:16384
	ds_read_b128 v[224:227], v198 offset:17408
	ds_read_b128 v[208:211], v198 offset:18432
	ds_read_b128 v[228:231], v198 offset:19456
	ds_read_b128 v[214:217], v198 offset:20480
	ds_read_b128 v[232:235], v198 offset:21504
	ds_read_b128 v[220:223], v198 offset:22528
	ds_read_b128 v[236:239], v198 offset:23552
	global_load_lds_dwordx4 v[186:187], off
	v_lshl_add_u64 v[188:189], s[56:57], 0, v[170:171]
	s_mov_b32 m0, s78
	s_addc_u32 s45, s57, 0
	global_load_lds_dwordx4 v[188:189], off
	v_lshl_add_u64 v[154:155], s[44:45], 0, v[172:173]
	s_mov_b32 m0, s79
	v_lshl_add_u64 v[190:191], s[58:59], 0, v[172:173]
	global_load_lds_dwordx4 v[154:155], off
	v_lshl_add_u64 v[154:155], s[44:45], 0, v[170:171]
	s_mov_b32 m0, s80
	v_lshl_add_u64 v[192:193], s[58:59], 0, v[170:171]
	global_load_lds_dwordx4 v[154:155], off
	s_mov_b32 m0, s49
	s_nop 0
	global_load_lds_dwordx4 v[190:191], off
	s_mov_b32 m0, s60
	s_nop 0
	global_load_lds_dwordx4 v[192:193], off
	s_waitcnt vmcnt(8)
	s_waitcnt lgkmcnt(0)
	s_barrier
	s_setprio 1
	s_waitcnt lgkmcnt(0)
	v_mov_b32_e32 v206, v224
	v_mov_b32_e32 v207, v225
	s_nop 1
	v_mfma_scale_f32_16x16x128_f8f6f4 v[86:89], v[20:25], v[202:207], v[86:89], v168, v226 op_sel_hi:[0,0,0] cbsz:2 blgp:2
	s_nop 1
	v_mfma_scale_f32_16x16x128_f8f6f4 v[82:85], v[14:19], v[202:207], v[82:85], v164, v226 op_sel_hi:[0,0,0] cbsz:2 blgp:2
	v_mov_b32_e32 v212, v228
	v_mov_b32_e32 v213, v229
	s_nop 1
	v_mfma_scale_f32_16x16x128_f8f6f4 v[78:81], v[20:25], v[208:213], v[78:81], v168, v230 op_sel_hi:[0,0,0] cbsz:2 blgp:2
	s_nop 1
	v_mfma_scale_f32_16x16x128_f8f6f4 v[74:77], v[14:19], v[208:213], v[74:77], v164, v230 op_sel_hi:[0,0,0] cbsz:2 blgp:2
	v_mov_b32_e32 v218, v232
	v_mov_b32_e32 v219, v233
	s_nop 1
	v_mfma_scale_f32_16x16x128_f8f6f4 v[70:73], v[20:25], v[214:219], v[70:73], v168, v234 op_sel_hi:[0,0,0] cbsz:2 blgp:2
	s_nop 1
	v_mfma_scale_f32_16x16x128_f8f6f4 v[58:61], v[14:19], v[214:219], v[58:61], v164, v234 op_sel_hi:[0,0,0] cbsz:2 blgp:2
	v_mov_b32_e32 v224, v236
	v_mov_b32_e32 v225, v237
	s_nop 1
	v_mfma_scale_f32_16x16x128_f8f6f4 v[42:45], v[20:25], v[220:225], v[42:45], v168, v238 op_sel_hi:[0,0,0] cbsz:2 blgp:2
	s_nop 1
	v_mfma_scale_f32_16x16x128_f8f6f4 v[34:37], v[14:19], v[220:225], v[34:37], v164, v238 op_sel_hi:[0,0,0] cbsz:2 blgp:2
	s_nop 1
	v_mfma_scale_f32_16x16x128_f8f6f4 v[66:69], v[8:13], v[202:207], v[66:69], v156, v226 op_sel_hi:[0,0,0] cbsz:2 blgp:2
	s_nop 1
	v_mfma_scale_f32_16x16x128_f8f6f4 v[62:65], v[2:7], v[202:207], v[62:65], v160, v226 op_sel_hi:[0,0,0] cbsz:2 blgp:2
	s_nop 1
	v_mfma_scale_f32_16x16x128_f8f6f4 v[54:57], v[8:13], v[208:213], v[54:57], v156, v230 op_sel_hi:[0,0,0] cbsz:2 blgp:2
	s_nop 1
	v_mfma_scale_f32_16x16x128_f8f6f4 v[50:53], v[2:7], v[208:213], v[50:53], v160, v230 op_sel_hi:[0,0,0] cbsz:2 blgp:2
	s_nop 1
	v_mfma_scale_f32_16x16x128_f8f6f4 v[46:49], v[8:13], v[214:219], v[46:49], v156, v234 op_sel_hi:[0,0,0] cbsz:2 blgp:2
	s_nop 1
	v_mfma_scale_f32_16x16x128_f8f6f4 v[38:41], v[2:7], v[214:219], v[38:41], v160, v234 op_sel_hi:[0,0,0] cbsz:2 blgp:2
	s_nop 1
	v_mfma_scale_f32_16x16x128_f8f6f4 v[30:33], v[8:13], v[220:225], v[30:33], v156, v238 op_sel_hi:[0,0,0] cbsz:2 blgp:2
	s_nop 1
	v_mfma_scale_f32_16x16x128_f8f6f4 v[26:29], v[2:7], v[220:225], v[26:29], v160, v238 op_sel_hi:[0,0,0] cbsz:2 blgp:2
	s_setprio 0
	s_barrier
	ds_read_b128 v[20:23], v199
	ds_read_b128 v[166:169], v199 offset:1024
	ds_read_b128 v[14:17], v199 offset:2048
	ds_read_b128 v[162:165], v199 offset:3072
	ds_read_b128 v[8:11], v200
	ds_read_b128 v[158:161], v200 offset:1024
	ds_read_b128 v[2:5], v200 offset:2048
	ds_read_b128 v[154:157], v200 offset:3072
	s_add_u32 s44, s58, 0xc0000
	s_addc_u32 s45, s59, 0
	s_mov_b32 m0, s61
	v_lshl_add_u64 v[6:7], s[44:45], 0, v[172:173]
	ds_read_b128 v[202:205], v198 offset:32768
	ds_read_b128 v[224:227], v198 offset:33792
	ds_read_b128 v[208:211], v198 offset:34816
	ds_read_b128 v[228:231], v198 offset:35840
	ds_read_b128 v[214:217], v198 offset:36864
	ds_read_b128 v[232:235], v198 offset:37888
	ds_read_b128 v[220:223], v198 offset:38912
	ds_read_b128 v[236:239], v198 offset:39936
	global_load_lds_dwordx4 v[6:7], off
	v_lshl_add_u64 v[6:7], s[44:45], 0, v[170:171]
	s_mov_b32 m0, s62
	s_nop 0
	global_load_lds_dwordx4 v[6:7], off
	s_waitcnt vmcnt(8)
	s_waitcnt lgkmcnt(0)
	s_barrier
	s_setprio 1
	s_waitcnt lgkmcnt(0)
	v_mov_b32_e32 v206, v224
	v_mov_b32_e32 v207, v225
	v_mov_b32_e32 v24, v166
	v_mov_b32_e32 v25, v167
	s_nop 1
	v_mfma_scale_f32_16x16x128_f8f6f4 v[150:153], v[20:25], v[202:207], v[150:153], v168, v226 op_sel_hi:[0,0,0] cbsz:2 blgp:2
	v_mov_b32_e32 v18, v162
	v_mov_b32_e32 v19, v163
	s_nop 1
	v_mfma_scale_f32_16x16x128_f8f6f4 v[146:149], v[14:19], v[202:207], v[146:149], v164, v226 op_sel_hi:[0,0,0] cbsz:2 blgp:2
	v_mov_b32_e32 v212, v228
	v_mov_b32_e32 v213, v229
	s_nop 1
	v_mfma_scale_f32_16x16x128_f8f6f4 v[142:145], v[20:25], v[208:213], v[142:145], v168, v230 op_sel_hi:[0,0,0] cbsz:2 blgp:2
	s_nop 1
	v_mfma_scale_f32_16x16x128_f8f6f4 v[138:141], v[14:19], v[208:213], v[138:141], v164, v230 op_sel_hi:[0,0,0] cbsz:2 blgp:2
	v_mov_b32_e32 v218, v232
	v_mov_b32_e32 v219, v233
	s_nop 1
	v_mfma_scale_f32_16x16x128_f8f6f4 v[134:137], v[20:25], v[214:219], v[134:137], v168, v234 op_sel_hi:[0,0,0] cbsz:2 blgp:2
	s_nop 1
	v_mfma_scale_f32_16x16x128_f8f6f4 v[122:125], v[14:19], v[214:219], v[122:125], v164, v234 op_sel_hi:[0,0,0] cbsz:2 blgp:2
	v_mov_b32_e32 v224, v236
	v_mov_b32_e32 v225, v237
	s_nop 1
	v_mfma_scale_f32_16x16x128_f8f6f4 v[106:109], v[20:25], v[220:225], v[106:109], v168, v238 op_sel_hi:[0,0,0] cbsz:2 blgp:2
	s_nop 1
	v_mfma_scale_f32_16x16x128_f8f6f4 v[98:101], v[14:19], v[220:225], v[98:101], v164, v238 op_sel_hi:[0,0,0] cbsz:2 blgp:2
	v_mov_b32_e32 v12, v158
	v_mov_b32_e32 v13, v159
	s_nop 1
	v_mfma_scale_f32_16x16x128_f8f6f4 v[130:133], v[8:13], v[202:207], v[130:133], v160, v226 op_sel_hi:[0,0,0] cbsz:2 blgp:2
	v_mov_b32_e32 v6, v154
	v_mov_b32_e32 v7, v155
	s_nop 1
	v_mfma_scale_f32_16x16x128_f8f6f4 v[126:129], v[2:7], v[202:207], v[126:129], v156, v226 op_sel_hi:[0,0,0] cbsz:2 blgp:2
	s_nop 1
	v_mfma_scale_f32_16x16x128_f8f6f4 v[118:121], v[8:13], v[208:213], v[118:121], v160, v230 op_sel_hi:[0,0,0] cbsz:2 blgp:2
	s_nop 1
	v_mfma_scale_f32_16x16x128_f8f6f4 v[114:117], v[2:7], v[208:213], v[114:117], v156, v230 op_sel_hi:[0,0,0] cbsz:2 blgp:2
	s_nop 1
	v_mfma_scale_f32_16x16x128_f8f6f4 v[110:113], v[8:13], v[214:219], v[110:113], v160, v234 op_sel_hi:[0,0,0] cbsz:2 blgp:2
	s_nop 1
	v_mfma_scale_f32_16x16x128_f8f6f4 v[102:105], v[2:7], v[214:219], v[102:105], v156, v234 op_sel_hi:[0,0,0] cbsz:2 blgp:2
	s_nop 1
	v_mfma_scale_f32_16x16x128_f8f6f4 v[94:97], v[8:13], v[220:225], v[94:97], v160, v238 op_sel_hi:[0,0,0] cbsz:2 blgp:2
	s_nop 1
	v_mfma_scale_f32_16x16x128_f8f6f4 v[90:93], v[2:7], v[220:225], v[90:93], v156, v238 op_sel_hi:[0,0,0] cbsz:2 blgp:2
	s_setprio 0
	s_barrier
	s_mov_b32 m0, s82
	v_lshl_add_u64 v[154:155], v[186:187], 0, s[14:15]
	s_add_u32 s44, s56, 0xc0080
	ds_read_b128 v[202:205], v198 offset:49152
	ds_read_b128 v[224:227], v198 offset:50176
	ds_read_b128 v[208:211], v198 offset:51200
	ds_read_b128 v[228:231], v198 offset:52224
	ds_read_b128 v[214:217], v198 offset:53248
	ds_read_b128 v[232:235], v198 offset:54272
	ds_read_b128 v[220:223], v198 offset:55296
	ds_read_b128 v[236:239], v198 offset:56320
	global_load_lds_dwordx4 v[154:155], off
	v_lshl_add_u64 v[154:155], v[188:189], 0, s[14:15]
	s_mov_b32 m0, s83
	s_addc_u32 s45, s57, 0
	global_load_lds_dwordx4 v[154:155], off
	v_lshl_add_u64 v[154:155], s[44:45], 0, v[172:173]
	s_mov_b32 m0, s84
	s_nop 0
	global_load_lds_dwordx4 v[154:155], off
	v_lshl_add_u64 v[154:155], s[44:45], 0, v[170:171]
	s_mov_b32 m0, s85
	s_nop 0
	global_load_lds_dwordx4 v[154:155], off
	v_lshl_add_u64 v[154:155], v[190:191], 0, s[14:15]
	s_mov_b32 m0, s67
	s_nop 0
	global_load_lds_dwordx4 v[154:155], off
	v_lshl_add_u64 v[154:155], v[192:193], 0, s[14:15]
	s_mov_b32 m0, s68
	s_nop 0
	global_load_lds_dwordx4 v[154:155], off
	s_waitcnt vmcnt(8)
	s_waitcnt lgkmcnt(0)
	s_barrier
	s_setprio 1
	s_waitcnt lgkmcnt(0)
	v_mov_b32_e32 v206, v224
	v_mov_b32_e32 v207, v225
	s_nop 1
	v_mfma_scale_f32_16x16x128_f8f6f4 v[86:89], v[20:25], v[202:207], v[86:89], v168, v226 op_sel_hi:[0,0,0] cbsz:2 blgp:2
	s_nop 1
	v_mfma_scale_f32_16x16x128_f8f6f4 v[82:85], v[14:19], v[202:207], v[82:85], v164, v226 op_sel_hi:[0,0,0] cbsz:2 blgp:2
	v_mov_b32_e32 v212, v228
	v_mov_b32_e32 v213, v229
	s_nop 1
	v_mfma_scale_f32_16x16x128_f8f6f4 v[78:81], v[20:25], v[208:213], v[78:81], v168, v230 op_sel_hi:[0,0,0] cbsz:2 blgp:2
	s_nop 1
	v_mfma_scale_f32_16x16x128_f8f6f4 v[74:77], v[14:19], v[208:213], v[74:77], v164, v230 op_sel_hi:[0,0,0] cbsz:2 blgp:2
	v_mov_b32_e32 v218, v232
	v_mov_b32_e32 v219, v233
	s_nop 1
	v_mfma_scale_f32_16x16x128_f8f6f4 v[70:73], v[20:25], v[214:219], v[70:73], v168, v234 op_sel_hi:[0,0,0] cbsz:2 blgp:2
	s_nop 1
	v_mfma_scale_f32_16x16x128_f8f6f4 v[58:61], v[14:19], v[214:219], v[58:61], v164, v234 op_sel_hi:[0,0,0] cbsz:2 blgp:2
	v_mov_b32_e32 v224, v236
	v_mov_b32_e32 v225, v237
	s_nop 1
	v_mfma_scale_f32_16x16x128_f8f6f4 v[42:45], v[20:25], v[220:225], v[42:45], v168, v238 op_sel_hi:[0,0,0] cbsz:2 blgp:2
	s_nop 1
	v_mfma_scale_f32_16x16x128_f8f6f4 v[34:37], v[14:19], v[220:225], v[34:37], v164, v238 op_sel_hi:[0,0,0] cbsz:2 blgp:2
	s_nop 1
	v_mfma_scale_f32_16x16x128_f8f6f4 v[66:69], v[8:13], v[202:207], v[66:69], v160, v226 op_sel_hi:[0,0,0] cbsz:2 blgp:2
	s_nop 1
	v_mfma_scale_f32_16x16x128_f8f6f4 v[62:65], v[2:7], v[202:207], v[62:65], v156, v226 op_sel_hi:[0,0,0] cbsz:2 blgp:2
	s_nop 1
	v_mfma_scale_f32_16x16x128_f8f6f4 v[54:57], v[8:13], v[208:213], v[54:57], v160, v230 op_sel_hi:[0,0,0] cbsz:2 blgp:2
	s_nop 1
	v_mfma_scale_f32_16x16x128_f8f6f4 v[50:53], v[2:7], v[208:213], v[50:53], v156, v230 op_sel_hi:[0,0,0] cbsz:2 blgp:2
	s_nop 1
	v_mfma_scale_f32_16x16x128_f8f6f4 v[46:49], v[8:13], v[214:219], v[46:49], v160, v234 op_sel_hi:[0,0,0] cbsz:2 blgp:2
	s_nop 1
	v_mfma_scale_f32_16x16x128_f8f6f4 v[38:41], v[2:7], v[214:219], v[38:41], v156, v234 op_sel_hi:[0,0,0] cbsz:2 blgp:2
	s_nop 1
	v_mfma_scale_f32_16x16x128_f8f6f4 v[30:33], v[8:13], v[220:225], v[30:33], v160, v238 op_sel_hi:[0,0,0] cbsz:2 blgp:2
	s_nop 1
	v_mfma_scale_f32_16x16x128_f8f6f4 v[26:29], v[2:7], v[220:225], v[26:29], v156, v238 op_sel_hi:[0,0,0] cbsz:2 blgp:2
	s_setprio 0
	s_barrier
	s_add_i32 s87, s87, 2
	s_add_u32 s54, s54, 0x100
	s_addc_u32 s55, s55, 0
	s_add_u32 s81, s81, 0x100
	s_addc_u32 s86, s86, 0
	s_cmp_lt_u32 s87, 46
	s_cbranch_scc1 .LBB0_786
	s_nop 15
	s_nop 15
	s_andn2_b64 vcc, exec, s[20:21]
	s_cbranch_vccnz .LBB0_789
	s_barrier

.LBB0_944:
	ds_read_b128 v[20:23], v196
	ds_read_b128 v[166:169], v196 offset:1024
	ds_read_b128 v[14:17], v196 offset:2048
	ds_read_b128 v[162:165], v196 offset:3072
	ds_read_b128 v[8:11], v197
	ds_read_b128 v[158:161], v197 offset:1024
	ds_read_b128 v[2:5], v197 offset:2048
	ds_read_b128 v[154:157], v197 offset:3072
	s_add_u32 s40, s38, 0xfff80080
	s_addc_u32 s41, s39, -1
	s_cmp_eq_u32 s64, 28
	s_cselect_b32 s43, s23, s41
	s_cselect_b32 s42, s60, s40
	s_cselect_b32 s41, s21, s63
	s_cselect_b32 s40, s61, s62
	s_add_u32 s94, s38, 0xfff80000
	s_addc_u32 s95, s39, -1
	ds_read_b128 v[186:189], v198
	ds_read_b128 v[190:193], v198 offset:1024
	ds_read_b128 v[200:203], v198 offset:2048
	ds_read_b128 v[216:219], v198 offset:3072
	ds_read_b128 v[206:209], v198 offset:4096
	ds_read_b128 v[220:223], v198 offset:5120
	ds_read_b128 v[212:215], v198 offset:6144
	ds_read_b128 v[224:227], v198 offset:7168
	v_lshl_add_u64 v[238:239], s[94:95], 0, v[178:179]
	v_lshl_add_u64 v[240:241], s[94:95], 0, v[180:181]
	v_lshl_add_u64 v[242:243], s[38:39], 0, v[178:179]
	v_lshl_add_u64 v[244:245], s[38:39], 0, v[180:181]
	s_waitcnt vmcnt(4)
	s_waitcnt lgkmcnt(0)
	s_barrier
	s_setprio 1
	s_waitcnt lgkmcnt(0)
	v_mov_b32_e32 v24, v166
	v_mov_b32_e32 v25, v167
	s_nop 1
	v_mfma_scale_f32_16x16x128_f8f6f4 v[150:153], v[20:25], v[186:191], v[150:153], v168, v192 op_sel_hi:[0,0,0] cbsz:2 blgp:2
	s_mov_b32 m0, s53
	s_nop 0
	global_load_lds_dwordx4 v[238:239], off
	v_mov_b32_e32 v18, v162
	v_mov_b32_e32 v19, v163
	s_nop 1
	v_mfma_scale_f32_16x16x128_f8f6f4 v[146:149], v[14:19], v[186:191], v[146:149], v164, v192 op_sel_hi:[0,0,0] cbsz:2 blgp:2
	v_mov_b32_e32 v204, v216
	v_mov_b32_e32 v205, v217
	s_nop 1
	v_mfma_scale_f32_16x16x128_f8f6f4 v[142:145], v[20:25], v[200:205], v[142:145], v168, v218 op_sel_hi:[0,0,0] cbsz:2 blgp:2
	s_nop 1
	v_mfma_scale_f32_16x16x128_f8f6f4 v[138:141], v[14:19], v[200:205], v[138:141], v164, v218 op_sel_hi:[0,0,0] cbsz:2 blgp:2
	v_mov_b32_e32 v210, v220
	v_mov_b32_e32 v211, v221
	s_nop 1
	v_mfma_scale_f32_16x16x128_f8f6f4 v[134:137], v[20:25], v[206:211], v[134:137], v168, v222 op_sel_hi:[0,0,0] cbsz:2 blgp:2
	s_mov_b32 m0, s54
	s_nop 0
	global_load_lds_dwordx4 v[240:241], off
	s_nop 1
	v_mfma_scale_f32_16x16x128_f8f6f4 v[130:133], v[14:19], v[206:211], v[130:133], v164, v222 op_sel_hi:[0,0,0] cbsz:2 blgp:2
	v_mov_b32_e32 v216, v224
	v_mov_b32_e32 v217, v225
	s_nop 1
	v_mfma_scale_f32_16x16x128_f8f6f4 v[126:129], v[20:25], v[212:217], v[126:129], v168, v226 op_sel_hi:[0,0,0] cbsz:2 blgp:2
	s_nop 1
	v_mfma_scale_f32_16x16x128_f8f6f4 v[122:125], v[14:19], v[212:217], v[122:125], v164, v226 op_sel_hi:[0,0,0] cbsz:2 blgp:2
	v_mov_b32_e32 v12, v158
	v_mov_b32_e32 v13, v159
	s_nop 1
	v_mfma_scale_f32_16x16x128_f8f6f4 v[118:121], v[8:13], v[186:191], v[118:121], v160, v192 op_sel_hi:[0,0,0] cbsz:2 blgp:2
	s_add_i32 m0, s37, 0xc000
	s_nop 0
	global_load_lds_dwordx4 v[242:243], off
	v_mov_b32_e32 v6, v154
	v_mov_b32_e32 v7, v155
	s_nop 1
	v_mfma_scale_f32_16x16x128_f8f6f4 v[114:117], v[2:7], v[186:191], v[114:117], v156, v192 op_sel_hi:[0,0,0] cbsz:2 blgp:2
	s_nop 1
	v_mfma_scale_f32_16x16x128_f8f6f4 v[110:113], v[8:13], v[200:205], v[110:113], v160, v218 op_sel_hi:[0,0,0] cbsz:2 blgp:2
	s_nop 1
	v_mfma_scale_f32_16x16x128_f8f6f4 v[106:109], v[2:7], v[200:205], v[106:109], v156, v218 op_sel_hi:[0,0,0] cbsz:2 blgp:2
	s_nop 1
	v_mfma_scale_f32_16x16x128_f8f6f4 v[102:105], v[8:13], v[206:211], v[102:105], v160, v222 op_sel_hi:[0,0,0] cbsz:2 blgp:2
	s_add_i32 m0, s37, 0xe000
	s_nop 0
	global_load_lds_dwordx4 v[244:245], off
	s_nop 1
	v_mfma_scale_f32_16x16x128_f8f6f4 v[98:101], v[2:7], v[206:211], v[98:101], v156, v222 op_sel_hi:[0,0,0] cbsz:2 blgp:2
	s_nop 1
	v_mfma_scale_f32_16x16x128_f8f6f4 v[94:97], v[8:13], v[212:217], v[94:97], v160, v226 op_sel_hi:[0,0,0] cbsz:2 blgp:2
	s_nop 1
	v_mfma_scale_f32_16x16x128_f8f6f4 v[90:93], v[2:7], v[212:217], v[90:93], v156, v226 op_sel_hi:[0,0,0] cbsz:2 blgp:2
	s_setprio 0
	s_barrier
	s_add_u32 s44, s40, 0x80000
	s_addc_u32 s45, s41, 0
	ds_read_b128 v[200:203], v198 offset:16384
	ds_read_b128 v[222:225], v198 offset:17408
	ds_read_b128 v[206:209], v198 offset:18432
	ds_read_b128 v[226:229], v198 offset:19456
	ds_read_b128 v[212:215], v198 offset:20480
	ds_read_b128 v[230:233], v198 offset:21504
	ds_read_b128 v[218:221], v198 offset:22528
	ds_read_b128 v[234:237], v198 offset:23552
	v_lshl_add_u64 v[186:187], s[40:41], 0, v[174:175]
	v_lshl_add_u64 v[188:189], s[40:41], 0, v[170:171]
	v_lshl_add_u64 v[190:191], s[42:43], 0, v[176:177]
	v_lshl_add_u64 v[192:193], s[42:43], 0, v[172:173]
	v_lshl_add_u64 v[238:239], s[44:45], 0, v[174:175]
	v_lshl_add_u64 v[240:241], s[44:45], 0, v[170:171]
	s_waitcnt vmcnt(2)
	s_waitcnt lgkmcnt(0)
	s_barrier
	s_setprio 1
	s_waitcnt lgkmcnt(0)
	v_mov_b32_e32 v204, v222
	v_mov_b32_e32 v205, v223
	s_nop 1
	v_mfma_scale_f32_16x16x128_f8f6f4 v[86:89], v[20:25], v[200:205], v[86:89], v168, v224 op_sel_hi:[0,0,0] cbsz:2 blgp:2
	s_add_i32 m0, s37, 0x10000
	s_nop 0
	global_load_lds_dwordx4 v[186:187], off
	s_nop 1
	v_mfma_scale_f32_16x16x128_f8f6f4 v[82:85], v[14:19], v[200:205], v[82:85], v164, v224 op_sel_hi:[0,0,0] cbsz:2 blgp:2
	v_mov_b32_e32 v210, v226
	v_mov_b32_e32 v211, v227
	s_nop 1
	v_mfma_scale_f32_16x16x128_f8f6f4 v[78:81], v[20:25], v[206:211], v[78:81], v168, v228 op_sel_hi:[0,0,0] cbsz:2 blgp:2
	s_nop 1
	v_mfma_scale_f32_16x16x128_f8f6f4 v[74:77], v[14:19], v[206:211], v[74:77], v164, v228 op_sel_hi:[0,0,0] cbsz:2 blgp:2
	v_mov_b32_e32 v216, v230
	v_mov_b32_e32 v217, v231
	s_nop 1
	v_mfma_scale_f32_16x16x128_f8f6f4 v[70:73], v[20:25], v[212:217], v[70:73], v168, v232 op_sel_hi:[0,0,0] cbsz:2 blgp:2
	s_add_i32 m0, s37, 0x12000
	s_nop 0
	global_load_lds_dwordx4 v[188:189], off
	s_nop 1
	v_mfma_scale_f32_16x16x128_f8f6f4 v[66:69], v[14:19], v[212:217], v[66:69], v164, v232 op_sel_hi:[0,0,0] cbsz:2 blgp:2
	v_mov_b32_e32 v222, v234
	v_mov_b32_e32 v223, v235
	s_nop 1
	v_mfma_scale_f32_16x16x128_f8f6f4 v[62:65], v[20:25], v[218:223], v[62:65], v168, v236 op_sel_hi:[0,0,0] cbsz:2 blgp:2
	s_nop 1
	v_mfma_scale_f32_16x16x128_f8f6f4 v[58:61], v[14:19], v[218:223], v[58:61], v164, v236 op_sel_hi:[0,0,0] cbsz:2 blgp:2
	s_nop 1
	v_mfma_scale_f32_16x16x128_f8f6f4 v[54:57], v[8:13], v[200:205], v[54:57], v160, v224 op_sel_hi:[0,0,0] cbsz:2 blgp:2
	s_add_i32 m0, s37, 0x14000
	s_nop 0
	global_load_lds_dwordx4 v[238:239], off
	s_nop 1
	v_mfma_scale_f32_16x16x128_f8f6f4 v[50:53], v[2:7], v[200:205], v[50:53], v156, v224 op_sel_hi:[0,0,0] cbsz:2 blgp:2
	s_nop 1
	v_mfma_scale_f32_16x16x128_f8f6f4 v[46:49], v[8:13], v[206:211], v[46:49], v160, v228 op_sel_hi:[0,0,0] cbsz:2 blgp:2
	s_nop 1
	v_mfma_scale_f32_16x16x128_f8f6f4 v[42:45], v[2:7], v[206:211], v[42:45], v156, v228 op_sel_hi:[0,0,0] cbsz:2 blgp:2
	s_nop 1
	v_mfma_scale_f32_16x16x128_f8f6f4 v[38:41], v[8:13], v[212:217], v[38:41], v160, v232 op_sel_hi:[0,0,0] cbsz:2 blgp:2
	s_add_i32 m0, s37, 0x16000
	s_nop 0
	global_load_lds_dwordx4 v[240:241], off
	s_nop 1
	v_mfma_scale_f32_16x16x128_f8f6f4 v[34:37], v[2:7], v[212:217], v[34:37], v156, v232 op_sel_hi:[0,0,0] cbsz:2 blgp:2
	s_nop 1
	v_mfma_scale_f32_16x16x128_f8f6f4 v[30:33], v[8:13], v[218:223], v[30:33], v160, v236 op_sel_hi:[0,0,0] cbsz:2 blgp:2
	s_nop 1
	v_mfma_scale_f32_16x16x128_f8f6f4 v[26:29], v[2:7], v[218:223], v[26:29], v156, v236 op_sel_hi:[0,0,0] cbsz:2 blgp:2
	s_setprio 0
	s_barrier
	s_add_i32 s44, 0, 0x18000
	s_add_i32 s45, 0, 0x1c000
	v_add_u32_e32 v2, s44, v1
	v_add_u32_e32 v6, s45, v1
	ds_read_b128 v[20:23], v2
	ds_read_b128 v[166:169], v2 offset:1024
	ds_read_b128 v[14:17], v2 offset:2048
	ds_read_b128 v[162:165], v2 offset:3072
	ds_read_b128 v[8:11], v6
	ds_read_b128 v[154:157], v6 offset:1024
	ds_read_b128 v[2:5], v6 offset:2048
	ds_read_b128 v[158:161], v6 offset:3072
	s_add_u32 s42, s42, 0x80000
	s_addc_u32 s43, s43, 0
	v_lshl_add_u64 v[238:239], s[42:43], 0, v[176:177]
	ds_read_b128 v[200:203], v198 offset:32768
	ds_read_b128 v[222:225], v198 offset:33792
	ds_read_b128 v[206:209], v198 offset:34816
	ds_read_b128 v[226:229], v198 offset:35840
	ds_read_b128 v[212:215], v198 offset:36864
	ds_read_b128 v[230:233], v198 offset:37888
	ds_read_b128 v[218:221], v198 offset:38912
	ds_read_b128 v[234:237], v198 offset:39936
	v_lshl_add_u64 v[240:241], s[42:43], 0, v[172:173]
	s_waitcnt vmcnt(4)
	s_waitcnt lgkmcnt(0)
	s_barrier
	s_setprio 1
	s_waitcnt lgkmcnt(0)
	v_mov_b32_e32 v204, v222
	v_mov_b32_e32 v205, v223
	v_mov_b32_e32 v24, v166
	v_mov_b32_e32 v25, v167
	s_nop 1
	v_mfma_scale_f32_16x16x128_f8f6f4 v[150:153], v[20:25], v[200:205], v[150:153], v168, v224 op_sel_hi:[0,0,0] cbsz:2 blgp:2
	s_mov_b32 m0, s37
	s_nop 0
	global_load_lds_dwordx4 v[190:191], off
	v_mov_b32_e32 v18, v162
	v_mov_b32_e32 v19, v163
	s_nop 1
	v_mfma_scale_f32_16x16x128_f8f6f4 v[146:149], v[14:19], v[200:205], v[146:149], v164, v224 op_sel_hi:[0,0,0] cbsz:2 blgp:2
	v_mov_b32_e32 v210, v226
	v_mov_b32_e32 v211, v227
	s_nop 1
	v_mfma_scale_f32_16x16x128_f8f6f4 v[142:145], v[20:25], v[206:211], v[142:145], v168, v228 op_sel_hi:[0,0,0] cbsz:2 blgp:2
	s_nop 1
	v_mfma_scale_f32_16x16x128_f8f6f4 v[138:141], v[14:19], v[206:211], v[138:141], v164, v228 op_sel_hi:[0,0,0] cbsz:2 blgp:2
	v_mov_b32_e32 v216, v230
	v_mov_b32_e32 v217, v231
	s_nop 1
	v_mfma_scale_f32_16x16x128_f8f6f4 v[134:137], v[20:25], v[212:217], v[134:137], v168, v232 op_sel_hi:[0,0,0] cbsz:2 blgp:2
	s_mov_b32 m0, s48
	s_nop 0
	global_load_lds_dwordx4 v[192:193], off
	s_nop 1
	v_mfma_scale_f32_16x16x128_f8f6f4 v[130:133], v[14:19], v[212:217], v[130:133], v164, v232 op_sel_hi:[0,0,0] cbsz:2 blgp:2
	v_mov_b32_e32 v222, v234
	v_mov_b32_e32 v223, v235
	s_nop 1
	v_mfma_scale_f32_16x16x128_f8f6f4 v[126:129], v[20:25], v[218:223], v[126:129], v168, v236 op_sel_hi:[0,0,0] cbsz:2 blgp:2
	s_nop 1
	v_mfma_scale_f32_16x16x128_f8f6f4 v[122:125], v[14:19], v[218:223], v[122:125], v164, v236 op_sel_hi:[0,0,0] cbsz:2 blgp:2
	v_mov_b32_e32 v12, v154
	v_mov_b32_e32 v13, v155
	s_nop 1
	v_mfma_scale_f32_16x16x128_f8f6f4 v[118:121], v[8:13], v[200:205], v[118:121], v156, v224 op_sel_hi:[0,0,0] cbsz:2 blgp:2
	s_mov_b32 m0, s49
	s_nop 0
	global_load_lds_dwordx4 v[238:239], off
	v_mov_b32_e32 v6, v158
	v_mov_b32_e32 v7, v159
	s_nop 1
	v_mfma_scale_f32_16x16x128_f8f6f4 v[114:117], v[2:7], v[200:205], v[114:117], v160, v224 op_sel_hi:[0,0,0] cbsz:2 blgp:2
	s_nop 1
	v_mfma_scale_f32_16x16x128_f8f6f4 v[110:113], v[8:13], v[206:211], v[110:113], v156, v228 op_sel_hi:[0,0,0] cbsz:2 blgp:2
	s_nop 1
	v_mfma_scale_f32_16x16x128_f8f6f4 v[106:109], v[2:7], v[206:211], v[106:109], v160, v228 op_sel_hi:[0,0,0] cbsz:2 blgp:2
	s_nop 1
	v_mfma_scale_f32_16x16x128_f8f6f4 v[102:105], v[8:13], v[212:217], v[102:105], v156, v232 op_sel_hi:[0,0,0] cbsz:2 blgp:2
	s_mov_b32 m0, s50
	s_nop 0
	global_load_lds_dwordx4 v[240:241], off
	s_nop 1
	v_mfma_scale_f32_16x16x128_f8f6f4 v[98:101], v[2:7], v[212:217], v[98:101], v160, v232 op_sel_hi:[0,0,0] cbsz:2 blgp:2
	s_nop 1
	v_mfma_scale_f32_16x16x128_f8f6f4 v[94:97], v[8:13], v[218:223], v[94:97], v156, v236 op_sel_hi:[0,0,0] cbsz:2 blgp:2
	s_nop 1
	v_mfma_scale_f32_16x16x128_f8f6f4 v[90:93], v[2:7], v[218:223], v[90:93], v160, v236 op_sel_hi:[0,0,0] cbsz:2 blgp:2
	s_setprio 0
	s_barrier
	s_add_u32 s40, s40, 0x80080
	s_addc_u32 s41, s41, 0
	ds_read_b128 v[200:203], v198 offset:49152
	ds_read_b128 v[222:225], v198 offset:50176
	ds_read_b128 v[206:209], v198 offset:51200
	ds_read_b128 v[226:229], v198 offset:52224
	ds_read_b128 v[212:215], v198 offset:53248
	ds_read_b128 v[230:233], v198 offset:54272
	ds_read_b128 v[218:221], v198 offset:55296
	ds_read_b128 v[234:237], v198 offset:56320
	v_lshl_add_u64 v[238:239], v[186:187], 0, s[12:13]
	v_lshl_add_u64 v[240:241], v[188:189], 0, s[12:13]
	v_lshl_add_u64 v[242:243], s[40:41], 0, v[174:175]
	v_lshl_add_u64 v[244:245], s[40:41], 0, v[170:171]
	s_waitcnt vmcnt(2)
	s_waitcnt lgkmcnt(0)
	s_barrier
	s_setprio 1
	s_waitcnt lgkmcnt(0)
	v_mov_b32_e32 v204, v222
	v_mov_b32_e32 v205, v223
	s_nop 1
	v_mfma_scale_f32_16x16x128_f8f6f4 v[86:89], v[20:25], v[200:205], v[86:89], v168, v224 op_sel_hi:[0,0,0] cbsz:2 blgp:2
	s_add_i32 m0, s37, 0x18000
	s_nop 0
	global_load_lds_dwordx4 v[238:239], off
	s_nop 1
	v_mfma_scale_f32_16x16x128_f8f6f4 v[82:85], v[14:19], v[200:205], v[82:85], v164, v224 op_sel_hi:[0,0,0] cbsz:2 blgp:2
	v_mov_b32_e32 v210, v226
	v_mov_b32_e32 v211, v227
	s_nop 1
	v_mfma_scale_f32_16x16x128_f8f6f4 v[78:81], v[20:25], v[206:211], v[78:81], v168, v228 op_sel_hi:[0,0,0] cbsz:2 blgp:2
	s_nop 1
	v_mfma_scale_f32_16x16x128_f8f6f4 v[74:77], v[14:19], v[206:211], v[74:77], v164, v228 op_sel_hi:[0,0,0] cbsz:2 blgp:2
	v_mov_b32_e32 v216, v230
	v_mov_b32_e32 v217, v231
	s_nop 1
	v_mfma_scale_f32_16x16x128_f8f6f4 v[70:73], v[20:25], v[212:217], v[70:73], v168, v232 op_sel_hi:[0,0,0] cbsz:2 blgp:2
	s_add_i32 m0, s37, 0x1a000
	s_nop 0
	global_load_lds_dwordx4 v[240:241], off
	s_nop 1
	v_mfma_scale_f32_16x16x128_f8f6f4 v[66:69], v[14:19], v[212:217], v[66:69], v164, v232 op_sel_hi:[0,0,0] cbsz:2 blgp:2
	v_mov_b32_e32 v222, v234
	v_mov_b32_e32 v223, v235
	s_nop 1
	v_mfma_scale_f32_16x16x128_f8f6f4 v[62:65], v[20:25], v[218:223], v[62:65], v168, v236 op_sel_hi:[0,0,0] cbsz:2 blgp:2
	s_nop 1
	v_mfma_scale_f32_16x16x128_f8f6f4 v[58:61], v[14:19], v[218:223], v[58:61], v164, v236 op_sel_hi:[0,0,0] cbsz:2 blgp:2
	s_nop 1
	v_mfma_scale_f32_16x16x128_f8f6f4 v[54:57], v[8:13], v[200:205], v[54:57], v156, v224 op_sel_hi:[0,0,0] cbsz:2 blgp:2
	s_add_i32 m0, s37, 0x1c000
	s_nop 0
	global_load_lds_dwordx4 v[242:243], off
	s_nop 1
	v_mfma_scale_f32_16x16x128_f8f6f4 v[50:53], v[2:7], v[200:205], v[50:53], v160, v224 op_sel_hi:[0,0,0] cbsz:2 blgp:2
	s_nop 1
	v_mfma_scale_f32_16x16x128_f8f6f4 v[46:49], v[8:13], v[206:211], v[46:49], v156, v228 op_sel_hi:[0,0,0] cbsz:2 blgp:2
	s_nop 1
	v_mfma_scale_f32_16x16x128_f8f6f4 v[42:45], v[2:7], v[206:211], v[42:45], v160, v228 op_sel_hi:[0,0,0] cbsz:2 blgp:2
	s_nop 1
	v_mfma_scale_f32_16x16x128_f8f6f4 v[38:41], v[8:13], v[212:217], v[38:41], v156, v232 op_sel_hi:[0,0,0] cbsz:2 blgp:2
	s_add_i32 m0, s37, 0x1e000
	s_nop 0
	global_load_lds_dwordx4 v[244:245], off
	s_nop 1
	v_mfma_scale_f32_16x16x128_f8f6f4 v[34:37], v[2:7], v[212:217], v[34:37], v160, v232 op_sel_hi:[0,0,0] cbsz:2 blgp:2
	s_nop 1
	v_mfma_scale_f32_16x16x128_f8f6f4 v[30:33], v[8:13], v[218:223], v[30:33], v156, v236 op_sel_hi:[0,0,0] cbsz:2 blgp:2
	s_nop 1
	v_mfma_scale_f32_16x16x128_f8f6f4 v[26:29], v[2:7], v[218:223], v[26:29], v160, v236 op_sel_hi:[0,0,0] cbsz:2 blgp:2
	s_setprio 0
	s_barrier
	s_add_i32 s64, s64, 2
	s_add_u32 s38, s38, 0x100
	s_addc_u32 s39, s39, 0
	s_add_u32 s62, s62, 0x100
	s_addc_u32 s63, s63, 0
	s_cmp_lt_u32 s64, 30
	s_cbranch_scc1 .LBB0_944
	s_nop 15
	s_nop 15
	s_andn2_b64 vcc, exec, s[14:15]
	s_cbranch_vccnz .LBB0_947
	s_barrier

.LBB0_1019:
	ds_read_b128 v[16:19], v183
	ds_read_b128 v[20:23], v183 offset:1024
	ds_read_b128 v[24:27], v183 offset:2048
	ds_read_b128 v[28:31], v183 offset:3072
	ds_read_b128 v[0:3], v184
	ds_read_b128 v[4:7], v184 offset:1024
	ds_read_b128 v[8:11], v184 offset:2048
	ds_read_b128 v[12:15], v184 offset:3072
	s_add_u32 s38, s36, 0xffe00080
	s_addc_u32 s39, s37, -1
	s_cmpk_eq_i32 s60, 0x7c
	s_cselect_b32 s41, s25, s39
	s_cselect_b32 s40, s56, s38
	s_cselect_b32 s39, s23, s59
	s_cselect_b32 s38, s57, s58
	v_lshl_add_u64 v[212:213], s[36:37], 0, v[164:165]
	s_add_i32 m0, s31, 0xc000
	ds_read_b128 v[172:175], v185
	ds_read_b128 v[176:179], v185 offset:1024
	ds_read_b128 v[188:191], v185 offset:2048
	ds_read_b128 v[192:195], v185 offset:3072
	ds_read_b128 v[196:199], v185 offset:4096
	ds_read_b128 v[200:203], v185 offset:5120
	ds_read_b128 v[204:207], v185 offset:6144
	ds_read_b128 v[208:211], v185 offset:7168
	global_load_lds_dwordx4 v[212:213], off
	v_lshl_add_u64 v[212:213], s[36:37], 0, v[166:167]
	s_add_i32 m0, s31, 0xe000
	s_nop 0
	global_load_lds_dwordx4 v[212:213], off
	s_waitcnt vmcnt(8)
	s_waitcnt lgkmcnt(0)
	s_barrier
	s_setprio 1
	s_waitcnt lgkmcnt(0)
	s_nop 1
	v_mfma_scale_f32_16x16x128_f8f6f4 v[156:159], v[16:23], v[172:179], v[156:159], v186, v186 op_sel_hi:[0,0,0]
	s_nop 1
	v_mfma_scale_f32_16x16x128_f8f6f4 v[152:155], v[24:31], v[172:179], v[152:155], v186, v186 op_sel_hi:[0,0,0]
	s_nop 1
	v_mfma_scale_f32_16x16x128_f8f6f4 v[148:151], v[16:23], v[188:195], v[148:151], v186, v186 op_sel_hi:[0,0,0]
	s_nop 1
	v_mfma_scale_f32_16x16x128_f8f6f4 v[144:147], v[24:31], v[188:195], v[144:147], v186, v186 op_sel_hi:[0,0,0]
	s_nop 1
	v_mfma_scale_f32_16x16x128_f8f6f4 v[140:143], v[16:23], v[196:203], v[140:143], v186, v186 op_sel_hi:[0,0,0]
	s_nop 1
	v_mfma_scale_f32_16x16x128_f8f6f4 v[124:127], v[24:31], v[196:203], v[124:127], v186, v186 op_sel_hi:[0,0,0]
	s_nop 1
	v_mfma_scale_f32_16x16x128_f8f6f4 v[116:119], v[16:23], v[204:211], v[116:119], v186, v186 op_sel_hi:[0,0,0]
	s_nop 1
	v_mfma_scale_f32_16x16x128_f8f6f4 v[108:111], v[24:31], v[204:211], v[108:111], v186, v186 op_sel_hi:[0,0,0]
	s_nop 1
	v_mfma_scale_f32_16x16x128_f8f6f4 v[136:139], v[0:7], v[172:179], v[136:139], v186, v186 op_sel_hi:[0,0,0]
	s_nop 1
	v_mfma_scale_f32_16x16x128_f8f6f4 v[132:135], v[8:15], v[172:179], v[132:135], v186, v186 op_sel_hi:[0,0,0]
	s_nop 1
	v_mfma_scale_f32_16x16x128_f8f6f4 v[128:131], v[0:7], v[188:195], v[128:131], v186, v186 op_sel_hi:[0,0,0]
	s_nop 1
	v_mfma_scale_f32_16x16x128_f8f6f4 v[120:123], v[8:15], v[188:195], v[120:123], v186, v186 op_sel_hi:[0,0,0]
	s_nop 1
	v_mfma_scale_f32_16x16x128_f8f6f4 v[112:115], v[0:7], v[196:203], v[112:115], v186, v186 op_sel_hi:[0,0,0]
	s_nop 1
	v_mfma_scale_f32_16x16x128_f8f6f4 v[104:107], v[8:15], v[196:203], v[104:107], v186, v186 op_sel_hi:[0,0,0]
	s_nop 1
	v_mfma_scale_f32_16x16x128_f8f6f4 v[100:103], v[0:7], v[204:211], v[100:103], v186, v186 op_sel_hi:[0,0,0]
	s_nop 1
	v_mfma_scale_f32_16x16x128_f8f6f4 v[96:99], v[8:15], v[204:211], v[96:99], v186, v186 op_sel_hi:[0,0,0]
	s_setprio 0
	s_barrier
	s_add_i32 s61, s53, s42
	v_lshl_add_u64 v[172:173], s[38:39], 0, v[162:163]
	s_mov_b32 m0, s61
	ds_read_b128 v[188:191], v185 offset:16384
	ds_read_b128 v[192:195], v185 offset:17408
	ds_read_b128 v[196:199], v185 offset:18432
	ds_read_b128 v[200:203], v185 offset:19456
	ds_read_b128 v[204:207], v185 offset:20480
	ds_read_b128 v[208:211], v185 offset:21504
	ds_read_b128 v[212:215], v185 offset:22528
	ds_read_b128 v[216:219], v185 offset:23552
	global_load_lds_dwordx4 v[172:173], off
	s_add_i32 m0, s61, 0x2000
	s_add_u32 s62, s38, 0x200000
	v_lshl_add_u64 v[174:175], s[38:39], 0, v[160:161]
	s_addc_u32 s63, s39, 0
	s_add_i32 s61, s54, s42
	global_load_lds_dwordx4 v[174:175], off
	v_lshl_add_u64 v[176:177], s[62:63], 0, v[162:163]
	s_mov_b32 m0, s61
	v_lshl_add_u64 v[178:179], s[40:41], 0, v[160:161]
	global_load_lds_dwordx4 v[176:177], off
	v_lshl_add_u64 v[176:177], s[62:63], 0, v[160:161]
	s_add_i32 m0, s61, 0x2000
	s_nop 0
	global_load_lds_dwordx4 v[176:177], off
	v_lshl_add_u64 v[176:177], s[40:41], 0, v[162:163]
	s_mov_b32 m0, s31
	s_nop 0
	global_load_lds_dwordx4 v[176:177], off
	s_mov_b32 m0, s44
	s_nop 0
	global_load_lds_dwordx4 v[178:179], off
	s_waitcnt vmcnt(8)
	s_waitcnt lgkmcnt(0)
	s_barrier
	s_setprio 1
	s_waitcnt lgkmcnt(0)
	s_nop 1
	v_mfma_scale_f32_16x16x128_f8f6f4 v[92:95], v[16:23], v[188:195], v[92:95], v186, v186 op_sel_hi:[0,0,0]
	s_nop 1
	v_mfma_scale_f32_16x16x128_f8f6f4 v[88:91], v[24:31], v[188:195], v[88:91], v186, v186 op_sel_hi:[0,0,0]
	s_nop 1
	v_mfma_scale_f32_16x16x128_f8f6f4 v[84:87], v[16:23], v[196:203], v[84:87], v186, v186 op_sel_hi:[0,0,0]
	s_nop 1
	v_mfma_scale_f32_16x16x128_f8f6f4 v[80:83], v[24:31], v[196:203], v[80:83], v186, v186 op_sel_hi:[0,0,0]
	s_nop 1
	v_mfma_scale_f32_16x16x128_f8f6f4 v[76:79], v[16:23], v[204:211], v[76:79], v186, v186 op_sel_hi:[0,0,0]
	s_nop 1
	v_mfma_scale_f32_16x16x128_f8f6f4 v[64:67], v[24:31], v[204:211], v[64:67], v186, v186 op_sel_hi:[0,0,0]
	s_nop 1
	v_mfma_scale_f32_16x16x128_f8f6f4 v[52:55], v[16:23], v[212:219], v[52:55], v186, v186 op_sel_hi:[0,0,0]
	s_nop 1
	v_mfma_scale_f32_16x16x128_f8f6f4 v[44:47], v[24:31], v[212:219], v[44:47], v186, v186 op_sel_hi:[0,0,0]
	s_nop 1
	v_mfma_scale_f32_16x16x128_f8f6f4 v[72:75], v[0:7], v[188:195], v[72:75], v186, v186 op_sel_hi:[0,0,0]
	s_nop 1
	v_mfma_scale_f32_16x16x128_f8f6f4 v[68:71], v[8:15], v[188:195], v[68:71], v186, v186 op_sel_hi:[0,0,0]
	s_nop 1
	v_mfma_scale_f32_16x16x128_f8f6f4 v[60:63], v[0:7], v[196:203], v[60:63], v186, v186 op_sel_hi:[0,0,0]
	s_nop 1
	v_mfma_scale_f32_16x16x128_f8f6f4 v[56:59], v[8:15], v[196:203], v[56:59], v186, v186 op_sel_hi:[0,0,0]
	s_nop 1
	v_mfma_scale_f32_16x16x128_f8f6f4 v[48:51], v[0:7], v[204:211], v[48:51], v186, v186 op_sel_hi:[0,0,0]
	s_nop 1
	v_mfma_scale_f32_16x16x128_f8f6f4 v[40:43], v[8:15], v[204:211], v[40:43], v186, v186 op_sel_hi:[0,0,0]
	s_nop 1
	v_mfma_scale_f32_16x16x128_f8f6f4 v[36:39], v[0:7], v[212:219], v[36:39], v186, v186 op_sel_hi:[0,0,0]
	s_nop 1
	v_mfma_scale_f32_16x16x128_f8f6f4 v[32:35], v[8:15], v[212:219], v[32:35], v186, v186 op_sel_hi:[0,0,0]
	s_setprio 0
	s_barrier
	s_add_i32 s61, 0, 0x18000
	s_add_i32 s62, 0, 0x1c000
	v_add_u32_e32 v12, s61, v181
	v_add_u32_e32 v28, s62, v181
	ds_read_b128 v[0:3], v12
	ds_read_b128 v[4:7], v12 offset:1024
	ds_read_b128 v[8:11], v12 offset:2048
	ds_read_b128 v[12:15], v12 offset:3072
	ds_read_b128 v[16:19], v28
	ds_read_b128 v[20:23], v28 offset:1024
	ds_read_b128 v[24:27], v28 offset:2048
	ds_read_b128 v[28:31], v28 offset:3072
	s_add_u32 s40, s40, 0x200000
	s_addc_u32 s41, s41, 0
	s_mov_b32 m0, s45
	v_lshl_add_u64 v[220:221], s[40:41], 0, v[162:163]
	ds_read_b128 v[188:191], v185 offset:32768
	ds_read_b128 v[192:195], v185 offset:33792
	ds_read_b128 v[196:199], v185 offset:34816
	ds_read_b128 v[200:203], v185 offset:35840
	ds_read_b128 v[204:207], v185 offset:36864
	ds_read_b128 v[208:211], v185 offset:37888
	ds_read_b128 v[212:215], v185 offset:38912
	ds_read_b128 v[216:219], v185 offset:39936
	global_load_lds_dwordx4 v[220:221], off
	v_lshl_add_u64 v[220:221], s[40:41], 0, v[160:161]
	s_mov_b32 m0, s46
	s_nop 0
	global_load_lds_dwordx4 v[220:221], off
	s_waitcnt vmcnt(8)
	s_waitcnt lgkmcnt(0)
	s_barrier
	s_setprio 1
	s_waitcnt lgkmcnt(0)
	s_nop 1
	v_mfma_scale_f32_16x16x128_f8f6f4 v[156:159], v[0:7], v[188:195], v[156:159], v186, v186 op_sel_hi:[0,0,0]
	s_nop 1
	v_mfma_scale_f32_16x16x128_f8f6f4 v[152:155], v[8:15], v[188:195], v[152:155], v186, v186 op_sel_hi:[0,0,0]
	s_nop 1
	v_mfma_scale_f32_16x16x128_f8f6f4 v[148:151], v[0:7], v[196:203], v[148:151], v186, v186 op_sel_hi:[0,0,0]
	s_nop 1
	v_mfma_scale_f32_16x16x128_f8f6f4 v[144:147], v[8:15], v[196:203], v[144:147], v186, v186 op_sel_hi:[0,0,0]
	s_nop 1
	v_mfma_scale_f32_16x16x128_f8f6f4 v[140:143], v[0:7], v[204:211], v[140:143], v186, v186 op_sel_hi:[0,0,0]
	s_nop 1
	v_mfma_scale_f32_16x16x128_f8f6f4 v[124:127], v[8:15], v[204:211], v[124:127], v186, v186 op_sel_hi:[0,0,0]
	s_nop 1
	v_mfma_scale_f32_16x16x128_f8f6f4 v[116:119], v[0:7], v[212:219], v[116:119], v186, v186 op_sel_hi:[0,0,0]
	s_nop 1
	v_mfma_scale_f32_16x16x128_f8f6f4 v[108:111], v[8:15], v[212:219], v[108:111], v186, v186 op_sel_hi:[0,0,0]
	s_nop 1
	v_mfma_scale_f32_16x16x128_f8f6f4 v[136:139], v[16:23], v[188:195], v[136:139], v186, v186 op_sel_hi:[0,0,0]
	s_nop 1
	v_mfma_scale_f32_16x16x128_f8f6f4 v[132:135], v[24:31], v[188:195], v[132:135], v186, v186 op_sel_hi:[0,0,0]
	s_nop 1
	v_mfma_scale_f32_16x16x128_f8f6f4 v[128:131], v[16:23], v[196:203], v[128:131], v186, v186 op_sel_hi:[0,0,0]
	s_nop 1
	v_mfma_scale_f32_16x16x128_f8f6f4 v[120:123], v[24:31], v[196:203], v[120:123], v186, v186 op_sel_hi:[0,0,0]
	s_nop 1
	v_mfma_scale_f32_16x16x128_f8f6f4 v[112:115], v[16:23], v[204:211], v[112:115], v186, v186 op_sel_hi:[0,0,0]
	s_nop 1
	v_mfma_scale_f32_16x16x128_f8f6f4 v[104:107], v[24:31], v[204:211], v[104:107], v186, v186 op_sel_hi:[0,0,0]
	s_nop 1
	v_mfma_scale_f32_16x16x128_f8f6f4 v[100:103], v[16:23], v[212:219], v[100:103], v186, v186 op_sel_hi:[0,0,0]
	s_nop 1
	v_mfma_scale_f32_16x16x128_f8f6f4 v[96:99], v[24:31], v[212:219], v[96:99], v186, v186 op_sel_hi:[0,0,0]
	s_setprio 0
	s_barrier
	s_add_i32 s40, s61, s42
	v_lshl_add_u64 v[172:173], v[172:173], 0, s[6:7]
	s_mov_b32 m0, s40
	ds_read_b128 v[188:191], v185 offset:49152
	ds_read_b128 v[192:195], v185 offset:50176
	ds_read_b128 v[196:199], v185 offset:51200
	ds_read_b128 v[200:203], v185 offset:52224
	ds_read_b128 v[204:207], v185 offset:53248
	ds_read_b128 v[208:211], v185 offset:54272
	ds_read_b128 v[212:215], v185 offset:55296
	ds_read_b128 v[216:219], v185 offset:56320
	global_load_lds_dwordx4 v[172:173], off
	s_add_i32 m0, s40, 0x2000
	s_add_u32 s38, s38, 0x200080
	v_lshl_add_u64 v[172:173], v[174:175], 0, s[6:7]
	s_addc_u32 s39, s39, 0
	s_add_i32 s40, s62, s42
	global_load_lds_dwordx4 v[172:173], off
	v_lshl_add_u64 v[172:173], s[38:39], 0, v[162:163]
	s_mov_b32 m0, s40
	s_nop 0
	global_load_lds_dwordx4 v[172:173], off
	v_lshl_add_u64 v[172:173], s[38:39], 0, v[160:161]
	s_add_i32 m0, s40, 0x2000
	s_nop 0
	global_load_lds_dwordx4 v[172:173], off
	v_lshl_add_u64 v[172:173], v[176:177], 0, s[6:7]
	s_mov_b32 m0, s51
	s_nop 0
	global_load_lds_dwordx4 v[172:173], off
	v_lshl_add_u64 v[172:173], v[178:179], 0, s[6:7]
	s_mov_b32 m0, s52
	s_nop 0
	global_load_lds_dwordx4 v[172:173], off
	s_waitcnt vmcnt(8)
	s_waitcnt lgkmcnt(0)
	s_barrier
	s_setprio 1
	s_waitcnt lgkmcnt(0)
	s_nop 1
	v_mfma_scale_f32_16x16x128_f8f6f4 v[92:95], v[0:7], v[188:195], v[92:95], v186, v186 op_sel_hi:[0,0,0]
	s_nop 1
	v_mfma_scale_f32_16x16x128_f8f6f4 v[88:91], v[8:15], v[188:195], v[88:91], v186, v186 op_sel_hi:[0,0,0]
	s_nop 1
	v_mfma_scale_f32_16x16x128_f8f6f4 v[84:87], v[0:7], v[196:203], v[84:87], v186, v186 op_sel_hi:[0,0,0]
	s_nop 1
	v_mfma_scale_f32_16x16x128_f8f6f4 v[80:83], v[8:15], v[196:203], v[80:83], v186, v186 op_sel_hi:[0,0,0]
	s_nop 1
	v_mfma_scale_f32_16x16x128_f8f6f4 v[76:79], v[0:7], v[204:211], v[76:79], v186, v186 op_sel_hi:[0,0,0]
	s_nop 1
	v_mfma_scale_f32_16x16x128_f8f6f4 v[64:67], v[8:15], v[204:211], v[64:67], v186, v186 op_sel_hi:[0,0,0]
	s_nop 1
	v_mfma_scale_f32_16x16x128_f8f6f4 v[52:55], v[0:7], v[212:219], v[52:55], v186, v186 op_sel_hi:[0,0,0]
	s_nop 1
	v_mfma_scale_f32_16x16x128_f8f6f4 v[44:47], v[8:15], v[212:219], v[44:47], v186, v186 op_sel_hi:[0,0,0]
	s_nop 1
	v_mfma_scale_f32_16x16x128_f8f6f4 v[72:75], v[16:23], v[188:195], v[72:75], v186, v186 op_sel_hi:[0,0,0]
	s_nop 1
	v_mfma_scale_f32_16x16x128_f8f6f4 v[68:71], v[24:31], v[188:195], v[68:71], v186, v186 op_sel_hi:[0,0,0]
	s_nop 1
	v_mfma_scale_f32_16x16x128_f8f6f4 v[60:63], v[16:23], v[196:203], v[60:63], v186, v186 op_sel_hi:[0,0,0]
	s_nop 1
	v_mfma_scale_f32_16x16x128_f8f6f4 v[56:59], v[24:31], v[196:203], v[56:59], v186, v186 op_sel_hi:[0,0,0]
	s_nop 1
	v_mfma_scale_f32_16x16x128_f8f6f4 v[48:51], v[16:23], v[204:211], v[48:51], v186, v186 op_sel_hi:[0,0,0]
	s_nop 1
	v_mfma_scale_f32_16x16x128_f8f6f4 v[40:43], v[24:31], v[204:211], v[40:43], v186, v186 op_sel_hi:[0,0,0]
	s_nop 1
	v_mfma_scale_f32_16x16x128_f8f6f4 v[36:39], v[16:23], v[212:219], v[36:39], v186, v186 op_sel_hi:[0,0,0]
	s_nop 1
	v_mfma_scale_f32_16x16x128_f8f6f4 v[32:35], v[24:31], v[212:219], v[32:35], v186, v186 op_sel_hi:[0,0,0]
	s_setprio 0
	s_barrier
	s_add_i32 s60, s60, 2
	s_add_u32 s36, s36, 0x100
	s_addc_u32 s37, s37, 0
	s_add_u32 s58, s58, 0x100
	s_addc_u32 s59, s59, 0
	s_cmpk_lt_u32 s60, 0x7e
	s_cbranch_scc1 .LBB0_1019
	s_nop 15
	s_nop 15
	s_andn2_b64 vcc, exec, s[12:13]
	s_cbranch_vccnz .LBB0_1022
	s_barrier
